# full stack + merge K-loop prefetch distance 2 (unrolled, second staging set parked-accumulator registers)
# baseline (speedup 1.0000x reference)
; template <int NI, class LA, class LB, class EP>
; __device__ __forceinline__ void gemm_tile(int K, LA loadA, LB loadB, EP epi, char* smem) {
;     ...
;   for (int kt = 0; kt < nk; ++kt) {
;     __syncthreads();
; #pragma unroll
;     for (int i = 0; i < 4; ++i) *(uint4*)&sA[(lr + 32 * i) * 72 + lc] = ra[i];
; #pragma unroll
;     for (int i = 0; i < NB; ++i) *(uint4*)&sB[(lr + 32 * i) * 72 + lc] = rb[i];
;     __syncthreads();
;     if (kt + 1 < nk) {
;       const int kk = (kt + 1) * 64 + lc;
; #pragma unroll
;       for (int i = 0; i < 4; ++i) ra[i] = loadA(lr + 32 * i, kk);
; #pragma unroll
;       for (int i = 0; i < NB; ++i) rb[i] = loadB(lr + 32 * i, kk);
;     }
; #pragma unroll
;     for (int s = 0; s < 4; ++s) {
;       h8 af[2], bf[NI];
; #pragma unroll
;       for (int mi = 0; mi < 2; ++mi)
;         af[mi] = *(const h8*)&sA[(wm * 64 + mi * 32 + (lane & 31)) * 72 + s * 16 + (lane >> 5) * 8];
; #pragma unroll
;       for (int ni = 0; ni < NI; ++ni)
;         bf[ni] = *(const h8*)&sB[(wn * (NI * 32) + ni * 32 + (lane & 31)) * 72 + s * 16 + (lane >> 5) * 8];
; #pragma unroll
;       for (int mi = 0; mi < 2; ++mi)
; #pragma unroll
;         for (int ni = 0; ni < NI; ++ni)
;           acc[mi][ni] = __builtin_amdgcn_mfma_f32_32x32x16_f16(af[mi], bf[ni], acc[mi][ni], 0, 0, 0);
;     }
.LBB0_1743:
	s_waitcnt vmcnt(63) expcnt(7) lgkmcnt(15)
	s_barrier
	s_waitcnt vmcnt(15)
	ds_write_b128 v172, v[192:195]
	s_waitcnt vmcnt(14)
	ds_write_b128 v172, v[196:199] offset:4608
	s_waitcnt vmcnt(13)
	ds_write_b128 v172, v[200:203] offset:9216
	s_waitcnt vmcnt(12)
	ds_write_b128 v172, v[204:207] offset:13824
	s_waitcnt vmcnt(11)
	ds_write_b128 v172, v[208:211] offset:18432
	s_waitcnt vmcnt(10)
	ds_write_b128 v172, v[212:215] offset:23040
	s_waitcnt vmcnt(9)
	ds_write_b128 v172, v[216:219] offset:27648
	s_waitcnt vmcnt(8)
	ds_write_b128 v172, v[220:223] offset:32256
	global_load_dwordx4 v[192:195], v[228:229], off offset:128
	global_load_dwordx4 v[196:199], v[230:231], off offset:128
	global_load_dwordx4 v[200:203], v[232:233], off offset:128
	global_load_dwordx4 v[204:207], v[234:235], off offset:128
	global_load_dwordx4 v[208:211], v[238:239], off offset:128
	global_load_dwordx4 v[212:215], v[240:241], off offset:128
	global_load_dwordx4 v[216:219], v[242:243], off offset:128
	global_load_dwordx4 v[220:223], v[244:245], off offset:128
	s_waitcnt lgkmcnt(0)
	s_barrier
	ds_read_b128 v[66:69], v162
	ds_read_b128 v[70:73], v163 offset:18432
	ds_read_b128 v[74:77], v162 offset:32
	ds_read_b128 v[78:81], v163 offset:18464
	ds_read_b128 v[82:85], v171 offset:18432
	ds_read_b128 v[174:177], v163 offset:23136
	s_waitcnt lgkmcnt(4)
	v_mfma_f32_32x32x16_f16 v[50:65], v[66:69], v[70:73], v[50:65]
	s_waitcnt lgkmcnt(1)
	v_mfma_f32_32x32x16_f16 v[34:49], v[66:69], v[82:85], v[34:49]
	ds_read_b128 v[66:69], v162 offset:4608
	ds_read_b128 v[86:89], v162 offset:4640
	s_waitcnt lgkmcnt(1)
	v_mfma_f32_32x32x16_f16 v[18:33], v[66:69], v[70:73], v[18:33]
	v_mfma_f32_32x32x16_f16 v[2:17], v[66:69], v[82:85], v[2:17]
	ds_read_b128 v[66:69], v163 offset:23072
	ds_read_b128 v[70:73], v163 offset:23104
	v_mfma_f32_32x32x16_f16 v[50:65], v[74:77], v[78:81], v[50:65]
	s_waitcnt lgkmcnt(1)
	v_mfma_f32_32x32x16_f16 v[34:49], v[74:77], v[66:69], v[34:49]
	v_mfma_f32_32x32x16_f16 v[18:33], v[86:89], v[78:81], v[18:33]
	v_mfma_f32_32x32x16_f16 v[2:17], v[86:89], v[66:69], v[2:17]
	ds_read_b128 v[66:69], v162 offset:64
	ds_read_b128 v[74:77], v163 offset:18496
	ds_read_b128 v[78:81], v162 offset:96
	ds_read_b128 v[82:85], v163 offset:18528
	ds_read_b128 v[86:89], v162 offset:4672
	ds_read_b128 v[178:181], v162 offset:4704
	s_waitcnt lgkmcnt(4)
	v_mfma_f32_32x32x16_f16 v[50:65], v[66:69], v[74:77], v[50:65]
	v_mfma_f32_32x32x16_f16 v[34:49], v[66:69], v[70:73], v[34:49]
	s_waitcnt lgkmcnt(1)
	v_mfma_f32_32x32x16_f16 v[18:33], v[86:89], v[74:77], v[18:33]
	v_mfma_f32_32x32x16_f16 v[2:17], v[86:89], v[70:73], v[2:17]
	v_mfma_f32_32x32x16_f16 v[50:65], v[78:81], v[82:85], v[50:65]
	v_mfma_f32_32x32x16_f16 v[34:49], v[78:81], v[174:177], v[34:49]
	s_waitcnt lgkmcnt(0)
	v_mfma_f32_32x32x16_f16 v[18:33], v[178:181], v[82:85], v[18:33]
	v_mfma_f32_32x32x16_f16 v[2:17], v[178:181], v[174:177], v[2:17]
	s_barrier
	s_waitcnt vmcnt(15)
	ds_write_b128 v172, v[130:133]
	s_waitcnt vmcnt(14)
	ds_write_b128 v172, v[134:137] offset:4608
	s_waitcnt vmcnt(13)
	ds_write_b128 v172, v[138:141] offset:9216
	s_waitcnt vmcnt(12)
	ds_write_b128 v172, v[142:145] offset:13824
	s_waitcnt vmcnt(11)
	ds_write_b128 v172, v[146:149] offset:18432
	s_waitcnt vmcnt(10)
	ds_write_b128 v172, v[150:153] offset:23040
	s_waitcnt vmcnt(9)
	ds_write_b128 v172, v[154:157] offset:27648
	s_waitcnt vmcnt(8)
	ds_write_b128 v172, v[158:161] offset:32256
	global_load_dwordx4 v[130:133], v[228:229], off offset:256
	global_load_dwordx4 v[134:137], v[230:231], off offset:256
	global_load_dwordx4 v[138:141], v[232:233], off offset:256
	global_load_dwordx4 v[142:145], v[234:235], off offset:256
	global_load_dwordx4 v[146:149], v[238:239], off offset:256
	global_load_dwordx4 v[150:153], v[240:241], off offset:256
	global_load_dwordx4 v[154:157], v[242:243], off offset:256
	global_load_dwordx4 v[158:161], v[244:245], off offset:256
	s_waitcnt lgkmcnt(0)
	s_barrier
	ds_read_b128 v[66:69], v162
	ds_read_b128 v[70:73], v163 offset:18432
	ds_read_b128 v[74:77], v162 offset:32
	ds_read_b128 v[78:81], v163 offset:18464
	ds_read_b128 v[82:85], v171 offset:18432
	ds_read_b128 v[174:177], v163 offset:23136
	s_waitcnt lgkmcnt(4)
	v_mfma_f32_32x32x16_f16 v[50:65], v[66:69], v[70:73], v[50:65]
	s_waitcnt lgkmcnt(1)
	v_mfma_f32_32x32x16_f16 v[34:49], v[66:69], v[82:85], v[34:49]
	ds_read_b128 v[66:69], v162 offset:4608
	ds_read_b128 v[86:89], v162 offset:4640
	s_waitcnt lgkmcnt(1)
	v_mfma_f32_32x32x16_f16 v[18:33], v[66:69], v[70:73], v[18:33]
	v_mfma_f32_32x32x16_f16 v[2:17], v[66:69], v[82:85], v[2:17]
	ds_read_b128 v[66:69], v163 offset:23072
	ds_read_b128 v[70:73], v163 offset:23104
	v_mfma_f32_32x32x16_f16 v[50:65], v[74:77], v[78:81], v[50:65]
	s_waitcnt lgkmcnt(1)
	v_mfma_f32_32x32x16_f16 v[34:49], v[74:77], v[66:69], v[34:49]
	v_mfma_f32_32x32x16_f16 v[18:33], v[86:89], v[78:81], v[18:33]
	v_mfma_f32_32x32x16_f16 v[2:17], v[86:89], v[66:69], v[2:17]
	ds_read_b128 v[66:69], v162 offset:64
	ds_read_b128 v[74:77], v163 offset:18496
	ds_read_b128 v[78:81], v162 offset:96
	ds_read_b128 v[82:85], v163 offset:18528
	ds_read_b128 v[86:89], v162 offset:4672
	ds_read_b128 v[178:181], v162 offset:4704
	s_waitcnt lgkmcnt(4)
	v_mfma_f32_32x32x16_f16 v[50:65], v[66:69], v[74:77], v[50:65]
	v_mfma_f32_32x32x16_f16 v[34:49], v[66:69], v[70:73], v[34:49]
	s_waitcnt lgkmcnt(1)
	v_mfma_f32_32x32x16_f16 v[18:33], v[86:89], v[74:77], v[18:33]
	v_mfma_f32_32x32x16_f16 v[2:17], v[86:89], v[70:73], v[2:17]
	v_mfma_f32_32x32x16_f16 v[50:65], v[78:81], v[82:85], v[50:65]
	v_mfma_f32_32x32x16_f16 v[34:49], v[78:81], v[174:177], v[34:49]
	s_waitcnt lgkmcnt(0)
	v_mfma_f32_32x32x16_f16 v[18:33], v[178:181], v[82:85], v[18:33]
	v_mfma_f32_32x32x16_f16 v[2:17], v[178:181], v[174:177], v[2:17]
	s_barrier
; template <int NI, class LA, class LB, class EP>
; __device__ __forceinline__ void gemm_tile(int K, LA loadA, LB loadB, EP epi, char* smem) {
;     ...
;   for (int kt = 0; kt < nk; ++kt) {
;     __syncthreads();
; #pragma unroll
;     for (int i = 0; i < 4; ++i) *(uint4*)&sA[(lr + 32 * i) * 72 + lc] = ra[i];
; #pragma unroll
;     for (int i = 0; i < NB; ++i) *(uint4*)&sB[(lr + 32 * i) * 72 + lc] = rb[i];
;     __syncthreads();
;     if (kt + 1 < nk) {
;       const int kk = (kt + 1) * 64 + lc;
; #pragma unroll
;       for (int i = 0; i < 4; ++i) ra[i] = loadA(lr + 32 * i, kk);
; #pragma unroll
;       for (int i = 0; i < NB; ++i) rb[i] = loadB(lr + 32 * i, kk);
;     }
; #pragma unroll
;     for (int s = 0; s < 4; ++s) {
;       h8 af[2], bf[NI];
; #pragma unroll
;       for (int mi = 0; mi < 2; ++mi)
;         af[mi] = *(const h8*)&sA[(wm * 64 + mi * 32 + (lane & 31)) * 72 + s * 16 + (lane >> 5) * 8];
; #pragma unroll
;       for (int ni = 0; ni < NI; ++ni)
;         bf[ni] = *(const h8*)&sB[(wn * (NI * 32) + ni * 32 + (lane & 31)) * 72 + s * 16 + (lane >> 5) * 8];
; #pragma unroll
;       for (int mi = 0; mi < 2; ++mi)
; #pragma unroll
;         for (int ni = 0; ni < NI; ++ni)
;           acc[mi][ni] = __builtin_amdgcn_mfma_f32_32x32x16_f16(af[mi], bf[ni], acc[mi][ni], 0, 0, 0);
;     }
	s_waitcnt vmcnt(15)
	ds_write_b128 v172, v[192:195]
	s_waitcnt vmcnt(14)
	ds_write_b128 v172, v[196:199] offset:4608
	s_waitcnt vmcnt(13)
	ds_write_b128 v172, v[200:203] offset:9216
	s_waitcnt vmcnt(12)
	ds_write_b128 v172, v[204:207] offset:13824
	s_waitcnt vmcnt(11)
	ds_write_b128 v172, v[208:211] offset:18432
	s_waitcnt vmcnt(10)
	ds_write_b128 v172, v[212:215] offset:23040
	s_waitcnt vmcnt(9)
	ds_write_b128 v172, v[216:219] offset:27648
	s_waitcnt vmcnt(8)
	ds_write_b128 v172, v[220:223] offset:32256
	global_load_dwordx4 v[192:195], v[228:229], off offset:384
	global_load_dwordx4 v[196:199], v[230:231], off offset:384
	global_load_dwordx4 v[200:203], v[232:233], off offset:384
	global_load_dwordx4 v[204:207], v[234:235], off offset:384
	global_load_dwordx4 v[208:211], v[238:239], off offset:384
	global_load_dwordx4 v[212:215], v[240:241], off offset:384
	global_load_dwordx4 v[216:219], v[242:243], off offset:384
	global_load_dwordx4 v[220:223], v[244:245], off offset:384
	s_waitcnt lgkmcnt(0)
	s_barrier
	ds_read_b128 v[66:69], v162
	ds_read_b128 v[70:73], v163 offset:18432
	ds_read_b128 v[74:77], v162 offset:32
	ds_read_b128 v[78:81], v163 offset:18464
	ds_read_b128 v[82:85], v171 offset:18432
	ds_read_b128 v[174:177], v163 offset:23136
	s_waitcnt lgkmcnt(4)
	v_mfma_f32_32x32x16_f16 v[50:65], v[66:69], v[70:73], v[50:65]
	s_waitcnt lgkmcnt(1)
	v_mfma_f32_32x32x16_f16 v[34:49], v[66:69], v[82:85], v[34:49]
	ds_read_b128 v[66:69], v162 offset:4608
	ds_read_b128 v[86:89], v162 offset:4640
	s_waitcnt lgkmcnt(1)
	v_mfma_f32_32x32x16_f16 v[18:33], v[66:69], v[70:73], v[18:33]
	v_mfma_f32_32x32x16_f16 v[2:17], v[66:69], v[82:85], v[2:17]
	ds_read_b128 v[66:69], v163 offset:23072
	ds_read_b128 v[70:73], v163 offset:23104
	v_mfma_f32_32x32x16_f16 v[50:65], v[74:77], v[78:81], v[50:65]
	s_waitcnt lgkmcnt(1)
	v_mfma_f32_32x32x16_f16 v[34:49], v[74:77], v[66:69], v[34:49]
	v_mfma_f32_32x32x16_f16 v[18:33], v[86:89], v[78:81], v[18:33]
	v_mfma_f32_32x32x16_f16 v[2:17], v[86:89], v[66:69], v[2:17]
	ds_read_b128 v[66:69], v162 offset:64
	ds_read_b128 v[74:77], v163 offset:18496
	ds_read_b128 v[78:81], v162 offset:96
	ds_read_b128 v[82:85], v163 offset:18528
	ds_read_b128 v[86:89], v162 offset:4672
	ds_read_b128 v[178:181], v162 offset:4704
	s_waitcnt lgkmcnt(4)
	v_mfma_f32_32x32x16_f16 v[50:65], v[66:69], v[74:77], v[50:65]
	v_mfma_f32_32x32x16_f16 v[34:49], v[66:69], v[70:73], v[34:49]
	s_waitcnt lgkmcnt(1)
	v_mfma_f32_32x32x16_f16 v[18:33], v[86:89], v[74:77], v[18:33]
	v_mfma_f32_32x32x16_f16 v[2:17], v[86:89], v[70:73], v[2:17]
	v_mfma_f32_32x32x16_f16 v[50:65], v[78:81], v[82:85], v[50:65]
	v_mfma_f32_32x32x16_f16 v[34:49], v[78:81], v[174:177], v[34:49]
	s_waitcnt lgkmcnt(0)
	v_mfma_f32_32x32x16_f16 v[18:33], v[178:181], v[82:85], v[18:33]
	v_mfma_f32_32x32x16_f16 v[2:17], v[178:181], v[174:177], v[2:17]
	s_barrier
	s_waitcnt vmcnt(15)
	ds_write_b128 v172, v[130:133]
	s_waitcnt vmcnt(14)
	ds_write_b128 v172, v[134:137] offset:4608
	s_waitcnt vmcnt(13)
	ds_write_b128 v172, v[138:141] offset:9216
	s_waitcnt vmcnt(12)
	ds_write_b128 v172, v[142:145] offset:13824
	s_waitcnt vmcnt(11)
	ds_write_b128 v172, v[146:149] offset:18432
	s_waitcnt vmcnt(10)
	ds_write_b128 v172, v[150:153] offset:23040
	s_waitcnt vmcnt(9)
	ds_write_b128 v172, v[154:157] offset:27648
	s_waitcnt vmcnt(8)
	ds_write_b128 v172, v[158:161] offset:32256
	global_load_dwordx4 v[130:133], v[228:229], off offset:512
	global_load_dwordx4 v[134:137], v[230:231], off offset:512
	global_load_dwordx4 v[138:141], v[232:233], off offset:512
	global_load_dwordx4 v[142:145], v[234:235], off offset:512
	global_load_dwordx4 v[146:149], v[238:239], off offset:512
	global_load_dwordx4 v[150:153], v[240:241], off offset:512
	global_load_dwordx4 v[154:157], v[242:243], off offset:512
	global_load_dwordx4 v[158:161], v[244:245], off offset:512
	s_waitcnt lgkmcnt(0)
	s_barrier
	ds_read_b128 v[66:69], v162
	ds_read_b128 v[70:73], v163 offset:18432
	ds_read_b128 v[74:77], v162 offset:32
	ds_read_b128 v[78:81], v163 offset:18464
	ds_read_b128 v[82:85], v171 offset:18432
	ds_read_b128 v[174:177], v163 offset:23136
	s_waitcnt lgkmcnt(4)
	v_mfma_f32_32x32x16_f16 v[50:65], v[66:69], v[70:73], v[50:65]
	s_waitcnt lgkmcnt(1)
	v_mfma_f32_32x32x16_f16 v[34:49], v[66:69], v[82:85], v[34:49]
	ds_read_b128 v[66:69], v162 offset:4608
	ds_read_b128 v[86:89], v162 offset:4640
	s_waitcnt lgkmcnt(1)
	v_mfma_f32_32x32x16_f16 v[18:33], v[66:69], v[70:73], v[18:33]
	v_mfma_f32_32x32x16_f16 v[2:17], v[66:69], v[82:85], v[2:17]
	ds_read_b128 v[66:69], v163 offset:23072
	ds_read_b128 v[70:73], v163 offset:23104
	v_mfma_f32_32x32x16_f16 v[50:65], v[74:77], v[78:81], v[50:65]
	s_waitcnt lgkmcnt(1)
	v_mfma_f32_32x32x16_f16 v[34:49], v[74:77], v[66:69], v[34:49]
	v_mfma_f32_32x32x16_f16 v[18:33], v[86:89], v[78:81], v[18:33]
	v_mfma_f32_32x32x16_f16 v[2:17], v[86:89], v[66:69], v[2:17]
	ds_read_b128 v[66:69], v162 offset:64
	ds_read_b128 v[74:77], v163 offset:18496
	ds_read_b128 v[78:81], v162 offset:96
	ds_read_b128 v[82:85], v163 offset:18528
	ds_read_b128 v[86:89], v162 offset:4672
	ds_read_b128 v[178:181], v162 offset:4704
	s_waitcnt lgkmcnt(4)
	v_mfma_f32_32x32x16_f16 v[50:65], v[66:69], v[74:77], v[50:65]
	v_mfma_f32_32x32x16_f16 v[34:49], v[66:69], v[70:73], v[34:49]
	s_waitcnt lgkmcnt(1)
	v_mfma_f32_32x32x16_f16 v[18:33], v[86:89], v[74:77], v[18:33]
	v_mfma_f32_32x32x16_f16 v[2:17], v[86:89], v[70:73], v[2:17]
	v_mfma_f32_32x32x16_f16 v[50:65], v[78:81], v[82:85], v[50:65]
	v_mfma_f32_32x32x16_f16 v[34:49], v[78:81], v[174:177], v[34:49]
	s_waitcnt lgkmcnt(0)
	v_mfma_f32_32x32x16_f16 v[18:33], v[178:181], v[82:85], v[18:33]
	v_mfma_f32_32x32x16_f16 v[2:17], v[178:181], v[174:177], v[2:17]
	s_barrier
; template <int NI, class LA, class LB, class EP>
; __device__ __forceinline__ void gemm_tile(int K, LA loadA, LB loadB, EP epi, char* smem) {
;     ...
;   for (int kt = 0; kt < nk; ++kt) {
;     __syncthreads();
; #pragma unroll
;     for (int i = 0; i < 4; ++i) *(uint4*)&sA[(lr + 32 * i) * 72 + lc] = ra[i];
; #pragma unroll
;     for (int i = 0; i < NB; ++i) *(uint4*)&sB[(lr + 32 * i) * 72 + lc] = rb[i];
;     __syncthreads();
;     if (kt + 1 < nk) {
;       const int kk = (kt + 1) * 64 + lc;
; #pragma unroll
;       for (int i = 0; i < 4; ++i) ra[i] = loadA(lr + 32 * i, kk);
; #pragma unroll
;       for (int i = 0; i < NB; ++i) rb[i] = loadB(lr + 32 * i, kk);
;     }
; #pragma unroll
;     for (int s = 0; s < 4; ++s) {
;       h8 af[2], bf[NI];
; #pragma unroll
;       for (int mi = 0; mi < 2; ++mi)
;         af[mi] = *(const h8*)&sA[(wm * 64 + mi * 32 + (lane & 31)) * 72 + s * 16 + (lane >> 5) * 8];
; #pragma unroll
;       for (int ni = 0; ni < NI; ++ni)
;         bf[ni] = *(const h8*)&sB[(wn * (NI * 32) + ni * 32 + (lane & 31)) * 72 + s * 16 + (lane >> 5) * 8];
; #pragma unroll
;       for (int mi = 0; mi < 2; ++mi)
; #pragma unroll
;         for (int ni = 0; ni < NI; ++ni)
;           acc[mi][ni] = __builtin_amdgcn_mfma_f32_32x32x16_f16(af[mi], bf[ni], acc[mi][ni], 0, 0, 0);
;     }
	s_waitcnt vmcnt(15)
	ds_write_b128 v172, v[192:195]
	s_waitcnt vmcnt(14)
	ds_write_b128 v172, v[196:199] offset:4608
	s_waitcnt vmcnt(13)
	ds_write_b128 v172, v[200:203] offset:9216
	s_waitcnt vmcnt(12)
	ds_write_b128 v172, v[204:207] offset:13824
	s_waitcnt vmcnt(11)
	ds_write_b128 v172, v[208:211] offset:18432
	s_waitcnt vmcnt(10)
	ds_write_b128 v172, v[212:215] offset:23040
	s_waitcnt vmcnt(9)
	ds_write_b128 v172, v[216:219] offset:27648
	s_waitcnt vmcnt(8)
	ds_write_b128 v172, v[220:223] offset:32256
	global_load_dwordx4 v[192:195], v[228:229], off offset:640
	global_load_dwordx4 v[196:199], v[230:231], off offset:640
	global_load_dwordx4 v[200:203], v[232:233], off offset:640
	global_load_dwordx4 v[204:207], v[234:235], off offset:640
	global_load_dwordx4 v[208:211], v[238:239], off offset:640
	global_load_dwordx4 v[212:215], v[240:241], off offset:640
	global_load_dwordx4 v[216:219], v[242:243], off offset:640
	global_load_dwordx4 v[220:223], v[244:245], off offset:640
	s_waitcnt lgkmcnt(0)
	s_barrier
	ds_read_b128 v[66:69], v162
	ds_read_b128 v[70:73], v163 offset:18432
	ds_read_b128 v[74:77], v162 offset:32
	ds_read_b128 v[78:81], v163 offset:18464
	ds_read_b128 v[82:85], v171 offset:18432
	ds_read_b128 v[174:177], v163 offset:23136
	s_waitcnt lgkmcnt(4)
	v_mfma_f32_32x32x16_f16 v[50:65], v[66:69], v[70:73], v[50:65]
	s_waitcnt lgkmcnt(1)
	v_mfma_f32_32x32x16_f16 v[34:49], v[66:69], v[82:85], v[34:49]
	ds_read_b128 v[66:69], v162 offset:4608
	ds_read_b128 v[86:89], v162 offset:4640
	s_waitcnt lgkmcnt(1)
	v_mfma_f32_32x32x16_f16 v[18:33], v[66:69], v[70:73], v[18:33]
	v_mfma_f32_32x32x16_f16 v[2:17], v[66:69], v[82:85], v[2:17]
	ds_read_b128 v[66:69], v163 offset:23072
	ds_read_b128 v[70:73], v163 offset:23104
	v_mfma_f32_32x32x16_f16 v[50:65], v[74:77], v[78:81], v[50:65]
	s_waitcnt lgkmcnt(1)
	v_mfma_f32_32x32x16_f16 v[34:49], v[74:77], v[66:69], v[34:49]
	v_mfma_f32_32x32x16_f16 v[18:33], v[86:89], v[78:81], v[18:33]
	v_mfma_f32_32x32x16_f16 v[2:17], v[86:89], v[66:69], v[2:17]
	ds_read_b128 v[66:69], v162 offset:64
	ds_read_b128 v[74:77], v163 offset:18496
	ds_read_b128 v[78:81], v162 offset:96
	ds_read_b128 v[82:85], v163 offset:18528
	ds_read_b128 v[86:89], v162 offset:4672
	ds_read_b128 v[178:181], v162 offset:4704
	s_waitcnt lgkmcnt(4)
	v_mfma_f32_32x32x16_f16 v[50:65], v[66:69], v[74:77], v[50:65]
	v_mfma_f32_32x32x16_f16 v[34:49], v[66:69], v[70:73], v[34:49]
	s_waitcnt lgkmcnt(1)
	v_mfma_f32_32x32x16_f16 v[18:33], v[86:89], v[74:77], v[18:33]
	v_mfma_f32_32x32x16_f16 v[2:17], v[86:89], v[70:73], v[2:17]
	v_mfma_f32_32x32x16_f16 v[50:65], v[78:81], v[82:85], v[50:65]
	v_mfma_f32_32x32x16_f16 v[34:49], v[78:81], v[174:177], v[34:49]
	s_waitcnt lgkmcnt(0)
	v_mfma_f32_32x32x16_f16 v[18:33], v[178:181], v[82:85], v[18:33]
	v_mfma_f32_32x32x16_f16 v[2:17], v[178:181], v[174:177], v[2:17]
	s_barrier
	s_waitcnt vmcnt(15)
	ds_write_b128 v172, v[130:133]
	s_waitcnt vmcnt(14)
	ds_write_b128 v172, v[134:137] offset:4608
	s_waitcnt vmcnt(13)
	ds_write_b128 v172, v[138:141] offset:9216
	s_waitcnt vmcnt(12)
	ds_write_b128 v172, v[142:145] offset:13824
	s_waitcnt vmcnt(11)
	ds_write_b128 v172, v[146:149] offset:18432
	s_waitcnt vmcnt(10)
	ds_write_b128 v172, v[150:153] offset:23040
	s_waitcnt vmcnt(9)
	ds_write_b128 v172, v[154:157] offset:27648
	s_waitcnt vmcnt(8)
	ds_write_b128 v172, v[158:161] offset:32256
	global_load_dwordx4 v[130:133], v[228:229], off offset:768
	global_load_dwordx4 v[134:137], v[230:231], off offset:768
	global_load_dwordx4 v[138:141], v[232:233], off offset:768
	global_load_dwordx4 v[142:145], v[234:235], off offset:768
	global_load_dwordx4 v[146:149], v[238:239], off offset:768
	global_load_dwordx4 v[150:153], v[240:241], off offset:768
	global_load_dwordx4 v[154:157], v[242:243], off offset:768
	global_load_dwordx4 v[158:161], v[244:245], off offset:768
	s_waitcnt lgkmcnt(0)
	s_barrier
	ds_read_b128 v[66:69], v162
	ds_read_b128 v[70:73], v163 offset:18432
	ds_read_b128 v[74:77], v162 offset:32
	ds_read_b128 v[78:81], v163 offset:18464
	ds_read_b128 v[82:85], v171 offset:18432
	ds_read_b128 v[174:177], v163 offset:23136
	s_waitcnt lgkmcnt(4)
	v_mfma_f32_32x32x16_f16 v[50:65], v[66:69], v[70:73], v[50:65]
	s_waitcnt lgkmcnt(1)
	v_mfma_f32_32x32x16_f16 v[34:49], v[66:69], v[82:85], v[34:49]
	ds_read_b128 v[66:69], v162 offset:4608
	ds_read_b128 v[86:89], v162 offset:4640
	s_waitcnt lgkmcnt(1)
	v_mfma_f32_32x32x16_f16 v[18:33], v[66:69], v[70:73], v[18:33]
	v_mfma_f32_32x32x16_f16 v[2:17], v[66:69], v[82:85], v[2:17]
	ds_read_b128 v[66:69], v163 offset:23072
	ds_read_b128 v[70:73], v163 offset:23104
	v_mfma_f32_32x32x16_f16 v[50:65], v[74:77], v[78:81], v[50:65]
	s_waitcnt lgkmcnt(1)
	v_mfma_f32_32x32x16_f16 v[34:49], v[74:77], v[66:69], v[34:49]
	v_mfma_f32_32x32x16_f16 v[18:33], v[86:89], v[78:81], v[18:33]
	v_mfma_f32_32x32x16_f16 v[2:17], v[86:89], v[66:69], v[2:17]
	ds_read_b128 v[66:69], v162 offset:64
	ds_read_b128 v[74:77], v163 offset:18496
	ds_read_b128 v[78:81], v162 offset:96
	ds_read_b128 v[82:85], v163 offset:18528
	ds_read_b128 v[86:89], v162 offset:4672
	ds_read_b128 v[178:181], v162 offset:4704
	s_waitcnt lgkmcnt(4)
	v_mfma_f32_32x32x16_f16 v[50:65], v[66:69], v[74:77], v[50:65]
	v_mfma_f32_32x32x16_f16 v[34:49], v[66:69], v[70:73], v[34:49]
	s_waitcnt lgkmcnt(1)
	v_mfma_f32_32x32x16_f16 v[18:33], v[86:89], v[74:77], v[18:33]
	v_mfma_f32_32x32x16_f16 v[2:17], v[86:89], v[70:73], v[2:17]
	v_mfma_f32_32x32x16_f16 v[50:65], v[78:81], v[82:85], v[50:65]
	v_mfma_f32_32x32x16_f16 v[34:49], v[78:81], v[174:177], v[34:49]
	s_waitcnt lgkmcnt(0)
	v_mfma_f32_32x32x16_f16 v[18:33], v[178:181], v[82:85], v[18:33]
	v_mfma_f32_32x32x16_f16 v[2:17], v[178:181], v[174:177], v[2:17]
	s_barrier
; template <int NI, class LA, class LB, class EP>
; __device__ __forceinline__ void gemm_tile(int K, LA loadA, LB loadB, EP epi, char* smem) {
;     ...
;   for (int kt = 0; kt < nk; ++kt) {
;     __syncthreads();
; #pragma unroll
;     for (int i = 0; i < 4; ++i) *(uint4*)&sA[(lr + 32 * i) * 72 + lc] = ra[i];
; #pragma unroll
;     for (int i = 0; i < NB; ++i) *(uint4*)&sB[(lr + 32 * i) * 72 + lc] = rb[i];
;     __syncthreads();
;     if (kt + 1 < nk) {
;       const int kk = (kt + 1) * 64 + lc;
; #pragma unroll
;       for (int i = 0; i < 4; ++i) ra[i] = loadA(lr + 32 * i, kk);
; #pragma unroll
;       for (int i = 0; i < NB; ++i) rb[i] = loadB(lr + 32 * i, kk);
;     }
; #pragma unroll
;     for (int s = 0; s < 4; ++s) {
;       h8 af[2], bf[NI];
; #pragma unroll
;       for (int mi = 0; mi < 2; ++mi)
;         af[mi] = *(const h8*)&sA[(wm * 64 + mi * 32 + (lane & 31)) * 72 + s * 16 + (lane >> 5) * 8];
; #pragma unroll
;       for (int ni = 0; ni < NI; ++ni)
;         bf[ni] = *(const h8*)&sB[(wn * (NI * 32) + ni * 32 + (lane & 31)) * 72 + s * 16 + (lane >> 5) * 8];
; #pragma unroll
;       for (int mi = 0; mi < 2; ++mi)
; #pragma unroll
;         for (int ni = 0; ni < NI; ++ni)
;           acc[mi][ni] = __builtin_amdgcn_mfma_f32_32x32x16_f16(af[mi], bf[ni], acc[mi][ni], 0, 0, 0);
;     }
	s_waitcnt vmcnt(15)
	ds_write_b128 v172, v[192:195]
	s_waitcnt vmcnt(14)
	ds_write_b128 v172, v[196:199] offset:4608
	s_waitcnt vmcnt(13)
	ds_write_b128 v172, v[200:203] offset:9216
	s_waitcnt vmcnt(12)
	ds_write_b128 v172, v[204:207] offset:13824
	s_waitcnt vmcnt(11)
	ds_write_b128 v172, v[208:211] offset:18432
	s_waitcnt vmcnt(10)
	ds_write_b128 v172, v[212:215] offset:23040
	s_waitcnt vmcnt(9)
	ds_write_b128 v172, v[216:219] offset:27648
	s_waitcnt vmcnt(8)
	ds_write_b128 v172, v[220:223] offset:32256
	s_waitcnt lgkmcnt(0)
	s_barrier
	ds_read_b128 v[66:69], v162
	ds_read_b128 v[70:73], v163 offset:18432
	ds_read_b128 v[74:77], v162 offset:32
	ds_read_b128 v[78:81], v163 offset:18464
	ds_read_b128 v[82:85], v171 offset:18432
	ds_read_b128 v[174:177], v163 offset:23136
	s_waitcnt lgkmcnt(4)
	v_mfma_f32_32x32x16_f16 v[50:65], v[66:69], v[70:73], v[50:65]
	s_waitcnt lgkmcnt(1)
	v_mfma_f32_32x32x16_f16 v[34:49], v[66:69], v[82:85], v[34:49]
	ds_read_b128 v[66:69], v162 offset:4608
	ds_read_b128 v[86:89], v162 offset:4640
	s_waitcnt lgkmcnt(1)
	v_mfma_f32_32x32x16_f16 v[18:33], v[66:69], v[70:73], v[18:33]
	v_mfma_f32_32x32x16_f16 v[2:17], v[66:69], v[82:85], v[2:17]
	ds_read_b128 v[66:69], v163 offset:23072
	ds_read_b128 v[70:73], v163 offset:23104
	v_mfma_f32_32x32x16_f16 v[50:65], v[74:77], v[78:81], v[50:65]
	s_waitcnt lgkmcnt(1)
	v_mfma_f32_32x32x16_f16 v[34:49], v[74:77], v[66:69], v[34:49]
	v_mfma_f32_32x32x16_f16 v[18:33], v[86:89], v[78:81], v[18:33]
	v_mfma_f32_32x32x16_f16 v[2:17], v[86:89], v[66:69], v[2:17]
	ds_read_b128 v[66:69], v162 offset:64
	ds_read_b128 v[74:77], v163 offset:18496
	ds_read_b128 v[78:81], v162 offset:96
	ds_read_b128 v[82:85], v163 offset:18528
	ds_read_b128 v[86:89], v162 offset:4672
	ds_read_b128 v[178:181], v162 offset:4704
	s_waitcnt lgkmcnt(4)
	v_mfma_f32_32x32x16_f16 v[50:65], v[66:69], v[74:77], v[50:65]
	v_mfma_f32_32x32x16_f16 v[34:49], v[66:69], v[70:73], v[34:49]
	s_waitcnt lgkmcnt(1)
	v_mfma_f32_32x32x16_f16 v[18:33], v[86:89], v[74:77], v[18:33]
	v_mfma_f32_32x32x16_f16 v[2:17], v[86:89], v[70:73], v[2:17]
	v_mfma_f32_32x32x16_f16 v[50:65], v[78:81], v[82:85], v[50:65]
	v_mfma_f32_32x32x16_f16 v[34:49], v[78:81], v[174:177], v[34:49]
	s_waitcnt lgkmcnt(0)
	v_mfma_f32_32x32x16_f16 v[18:33], v[178:181], v[82:85], v[18:33]
	v_mfma_f32_32x32x16_f16 v[2:17], v[178:181], v[174:177], v[2:17]
	s_barrier
	s_waitcnt vmcnt(7)
	ds_write_b128 v172, v[130:133]
	s_waitcnt vmcnt(6)
	ds_write_b128 v172, v[134:137] offset:4608
	s_waitcnt vmcnt(5)
	ds_write_b128 v172, v[138:141] offset:9216
	s_waitcnt vmcnt(4)
	ds_write_b128 v172, v[142:145] offset:13824
	s_waitcnt vmcnt(3)
	ds_write_b128 v172, v[146:149] offset:18432
	s_waitcnt vmcnt(2)
	ds_write_b128 v172, v[150:153] offset:23040
	s_waitcnt vmcnt(1)
	ds_write_b128 v172, v[154:157] offset:27648
	s_waitcnt vmcnt(0)
	ds_write_b128 v172, v[158:161] offset:32256
	s_waitcnt lgkmcnt(0)
	s_barrier
	ds_read_b128 v[66:69], v162 offset:4608
	ds_read_b128 v[70:73], v171 offset:18432
	ds_read_b128 v[74:77], v162
	ds_read_b128 v[78:81], v162 offset:32
	ds_read_b128 v[82:85], v163 offset:18432
	ds_read_b128 v[86:89], v163 offset:18464
	s_waitcnt lgkmcnt(1)
	v_mfma_f32_32x32x16_f16 v[50:65], v[74:77], v[82:85], v[50:65]
	s_lshl_b32 s2, s56, 11
	s_add_u32 s2, s52, s2
	s_addc_u32 s3, s53, 0
	v_lshlrev_b32_e32 v0, 1, v0
	s_add_i32 s56, s56, 1
	s_add_u32 s38, s38, 0x100000
	s_addc_u32 s39, s39, 0
	v_mfma_f32_32x32x16_f16 v[34:49], v[74:77], v[70:73], v[34:49]
	s_cmp_lg_u32 s56, 3
	v_mfma_f32_32x32x16_f16 v[18:33], v[66:69], v[82:85], v[18:33]
	v_mfma_f32_32x32x16_f16 v[2:17], v[66:69], v[70:73], v[2:17]
	ds_read_b128 v[66:69], v162 offset:4640
	ds_read_b128 v[70:73], v163 offset:23072
	s_waitcnt lgkmcnt(2)
	v_mfma_f32_32x32x16_f16 v[50:65], v[78:81], v[86:89], v[50:65]
	s_waitcnt lgkmcnt(0)
	v_mfma_f32_32x32x16_f16 v[34:49], v[78:81], v[70:73], v[34:49]
	v_mfma_f32_32x32x16_f16 v[18:33], v[66:69], v[86:89], v[18:33]
	v_mfma_f32_32x32x16_f16 v[2:17], v[66:69], v[70:73], v[2:17]
	ds_read_b128 v[66:69], v162 offset:64
	ds_read_b128 v[70:73], v162 offset:4672
	ds_read_b128 v[74:77], v163 offset:18496
	ds_read_b128 v[78:81], v163 offset:23104
	s_waitcnt lgkmcnt(1)
	v_mfma_f32_32x32x16_f16 v[50:65], v[66:69], v[74:77], v[50:65]
	s_waitcnt lgkmcnt(0)
	v_mfma_f32_32x32x16_f16 v[34:49], v[66:69], v[78:81], v[34:49]
	v_mfma_f32_32x32x16_f16 v[18:33], v[70:73], v[74:77], v[18:33]
	v_mfma_f32_32x32x16_f16 v[2:17], v[70:73], v[78:81], v[2:17]
	ds_read_b128 v[66:69], v162 offset:96
	ds_read_b128 v[70:73], v162 offset:4704
	ds_read_b128 v[74:77], v163 offset:18528
	ds_read_b128 v[78:81], v163 offset:23136
	s_waitcnt lgkmcnt(1)
	v_mfma_f32_32x32x16_f16 v[50:65], v[66:69], v[74:77], v[50:65]
	s_waitcnt lgkmcnt(0)
	v_mfma_f32_32x32x16_f16 v[34:49], v[66:69], v[78:81], v[34:49]
	v_mfma_f32_32x32x16_f16 v[18:33], v[70:73], v[74:77], v[18:33]
	v_mfma_f32_32x32x16_f16 v[2:17], v[70:73], v[78:81], v[2:17]
	v_mov_b32_e32 v228, 0x11fe4
	v_mov_b32_e32 v229, 0x100
	v_mov_b32_e32 v230, 2
	v_mov_b32_e32 v231, 0x3727c5ac
	v_mov_b32_e32 v232, 0x11fa0
	v_mov_b32_e32 v233, 0x80000
	v_mov_b32_e32 v234, 0x1d0000
	v_mov_b32_e32 v235, 0xa800
	v_mov_b32_e32 v238, 0x4000
	v_mov_b32_e32 v239, 0x4400
	v_mov_b32_e32 v240, 0x4800
	v_mov_b32_e32 v241, 0x4c00
	v_mov_b32_e32 v242, 0xf149f2ca
	v_mov_b32_e32 v243, 0x200
	v_mov_b32_e32 v244, 0x400
	v_mov_b32_e32 v245, 0x600
	ds_read_b128 v[130:133], v90
	ds_read_b128 v[134:137], v90 offset:4096
	ds_read_b128 v[138:141], v90 offset:8192
	ds_read_b128 v[142:145], v90 offset:12288
	ds_read_b128 v[146:149], v90 offset:16384
	ds_read_b128 v[150:153], v90 offset:20480
	ds_read_b128 v[154:157], v90 offset:24576
	ds_read_b128 v[158:161], v90 offset:28672
	s_waitcnt lgkmcnt(0)
; __device__ __forceinline__ float sigmoidf_(float x) { return 1.f / (1.f + __expf(-x)); }
; template <int NI, class LA, class LB, class EP>
; __device__ __forceinline__ void gemm_tile(int K, LA loadA, LB loadB, EP epi, char* smem) {
;     ...
; #pragma unroll
;   for (int mi = 0; mi < 2; ++mi)
; #pragma unroll
;     for (int ni = 0; ni < NI; ++ni)
; #pragma unroll
;       for (int r = 0; r < 16; ++r) {
;         const int row = wm * 64 + mi * 32 + (r & 3) + 8 * (r >> 2) + 4 * (lane >> 5);
;         const int col = wn * (NI * 32) + ni * 32 + (lane & 31);
;         epi(mi, ni, r, row, col, acc[mi][ni][r]);
; __device__ __forceinline__ void phase_merge(const KP& p, char* smem, int* q, int xcc) {
;     ...
;           [&](int mi, int ni, int r, int row, int col, float v) {
;             const float gz = (float)G[(size_t)row * NU + col];
;             tot[mi][ni][r] += sigmoidf_(gz) * v;
;           },
	v_lshrrev_b32_e32 v94, 7, v224
	v_lshlrev_b32_e32 v94, 4, v94
	v_bfe_u32 v95, v224, 5, 1
	v_add_u32_e32 v94, v94, v95
	v_mul_u32_u24_e32 v94, 0xe800, v94
	v_bfe_u32 v95, v224, 6, 1
	v_lshl_add_u32 v94, v95, 7, v94
	v_and_b32_e32 v95, 31, v224
	v_lshl_add_u32 v94, v95, 1, v94
	s_mov_b64 s[40:41], s[2:3]
	v_mov_b32_e32 v96, v94
	global_load_ushort v192, v96, s[40:41]
	v_add_u32_e32 v96, 0x3a00, v94
	global_load_ushort v193, v96, s[40:41]
	v_add_u32_e32 v96, 0x7400, v94
	global_load_ushort v194, v96, s[40:41]
	v_add_u32_e32 v96, 0xae00, v94
	global_load_ushort v195, v96, s[40:41]
	v_add_u32_e32 v96, 0x1d000, v94
	global_load_ushort v196, v96, s[40:41]
	v_add_u32_e32 v96, 0x20a00, v94
	global_load_ushort v197, v96, s[40:41]
	v_add_u32_e32 v96, 0x24400, v94
	global_load_ushort v198, v96, s[40:41]
	v_add_u32_e32 v96, 0x27e00, v94
	global_load_ushort v199, v96, s[40:41]
	v_add_u32_e32 v96, 0x3a000, v94
	global_load_ushort v200, v96, s[40:41]
	v_add_u32_e32 v96, 0x3da00, v94
	global_load_ushort v201, v96, s[40:41]
	v_add_u32_e32 v96, 0x41400, v94
	global_load_ushort v202, v96, s[40:41]
	v_add_u32_e32 v96, 0x44e00, v94
	global_load_ushort v203, v96, s[40:41]
	v_add_u32_e32 v96, 0x57000, v94
	global_load_ushort v204, v96, s[40:41]
	v_add_u32_e32 v96, 0x5aa00, v94
	global_load_ushort v205, v96, s[40:41]
	v_add_u32_e32 v96, 0x5e400, v94
	global_load_ushort v206, v96, s[40:41]
	v_add_u32_e32 v96, 0x61e00, v94
	global_load_ushort v207, v96, s[40:41]
	v_mov_b32_e32 v96, v94
	global_load_ushort v208, v96, s[40:41] offset:64
	v_add_u32_e32 v96, 0x3a00, v94
	global_load_ushort v209, v96, s[40:41] offset:64
	v_add_u32_e32 v96, 0x7400, v94
	global_load_ushort v210, v96, s[40:41] offset:64
	v_add_u32_e32 v96, 0xae00, v94
	global_load_ushort v211, v96, s[40:41] offset:64
	v_add_u32_e32 v96, 0x1d000, v94
	global_load_ushort v212, v96, s[40:41] offset:64
	v_add_u32_e32 v96, 0x20a00, v94
	global_load_ushort v213, v96, s[40:41] offset:64
	v_add_u32_e32 v96, 0x24400, v94
	global_load_ushort v214, v96, s[40:41] offset:64
	v_add_u32_e32 v96, 0x27e00, v94
	global_load_ushort v215, v96, s[40:41] offset:64
	v_add_u32_e32 v96, 0x3a000, v94
	global_load_ushort v216, v96, s[40:41] offset:64
	v_add_u32_e32 v96, 0x3da00, v94
	global_load_ushort v217, v96, s[40:41] offset:64
	v_add_u32_e32 v96, 0x41400, v94
	global_load_ushort v218, v96, s[40:41] offset:64
	v_add_u32_e32 v96, 0x44e00, v94
	global_load_ushort v219, v96, s[40:41] offset:64
	v_add_u32_e32 v96, 0x57000, v94
	global_load_ushort v220, v96, s[40:41] offset:64
	v_add_u32_e32 v96, 0x5aa00, v94
	global_load_ushort v221, v96, s[40:41] offset:64
	v_add_u32_e32 v96, 0x5e400, v94
	global_load_ushort v222, v96, s[40:41] offset:64
	v_add_u32_e32 v96, 0x61e00, v94
	global_load_ushort v223, v96, s[40:41] offset:64
	s_nop 7
	s_waitcnt vmcnt(30)
	v_cvt_f32_f16_e32 v68, v192
	v_cvt_f32_f16_e32 v69, v193
	v_add_u32_e32 v96, 0x74000, v94
	global_load_ushort v192, v96, s[40:41]
	v_add_u32_e32 v96, 0x77a00, v94
	global_load_ushort v193, v96, s[40:41]
	v_mul_f32_e32 v68, 0xbfb8aa3b, v68
	v_mul_f32_e32 v69, 0xbfb8aa3b, v69
	v_exp_f32_e32 v68, v68
	v_exp_f32_e32 v69, v69
	s_nop 0
	v_pk_add_f32 v[68:69], v[68:69], 1.0 op_sel_hi:[1,0]
	s_nop 0
	v_div_scale_f32 v70, s[2:3], v69, v69, 1.0
	v_rcp_f32_e32 v71, v70
	s_nop 0
	v_fma_f32 v72, -v70, v71, 1.0
	v_fmac_f32_e32 v71, v72, v71
	v_div_scale_f32 v72, vcc, 1.0, v69, 1.0
	v_mul_f32_e32 v73, v72, v71
	v_fma_f32 v74, -v70, v73, v72
	v_fmac_f32_e32 v73, v74, v71
	v_fma_f32 v70, -v70, v73, v72
	v_div_fmas_f32 v70, v70, v71, v73
	v_div_fixup_f32 v69, v70, v69, 1.0
	v_div_scale_f32 v70, s[2:3], v68, v68, 1.0
	v_rcp_f32_e32 v71, v70
	s_nop 0
	v_fma_f32 v72, -v70, v71, 1.0
	v_fmac_f32_e32 v71, v72, v71
	v_div_scale_f32 v72, vcc, 1.0, v68, 1.0
	v_mul_f32_e32 v73, v72, v71
	v_fma_f32 v74, -v70, v73, v72
	v_fmac_f32_e32 v73, v74, v71
	v_fma_f32 v70, -v70, v73, v72
	v_div_fmas_f32 v70, v70, v71, v73
	v_div_fixup_f32 v68, v70, v68, 1.0
	v_pk_fma_f32 v[160:161], v[50:51], v[68:69], v[160:161]
	s_waitcnt vmcnt(30)
	v_cvt_f32_f16_e32 v68, v194
	v_cvt_f32_f16_e32 v69, v195
	v_add_u32_e32 v96, 0x7b400, v94
	global_load_ushort v194, v96, s[40:41]
	v_add_u32_e32 v96, 0x7ee00, v94
	global_load_ushort v195, v96, s[40:41]
	v_mul_f32_e32 v68, 0xbfb8aa3b, v68
	v_mul_f32_e32 v69, 0xbfb8aa3b, v69
	v_exp_f32_e32 v68, v68
	v_exp_f32_e32 v69, v69
	s_nop 0
	v_pk_add_f32 v[68:69], v[68:69], 1.0 op_sel_hi:[1,0]
	s_nop 0
	v_div_scale_f32 v70, s[2:3], v69, v69, 1.0
	v_rcp_f32_e32 v71, v70
	s_nop 0
	v_fma_f32 v72, -v70, v71, 1.0
	v_fmac_f32_e32 v71, v72, v71
	v_div_scale_f32 v72, vcc, 1.0, v69, 1.0
	v_mul_f32_e32 v73, v72, v71
	v_fma_f32 v74, -v70, v73, v72
	v_fmac_f32_e32 v73, v74, v71
	v_fma_f32 v70, -v70, v73, v72
	v_div_fmas_f32 v70, v70, v71, v73
	v_div_fixup_f32 v69, v70, v69, 1.0
	v_div_scale_f32 v70, s[2:3], v68, v68, 1.0
	v_rcp_f32_e32 v71, v70
	s_nop 0
	v_fma_f32 v72, -v70, v71, 1.0
	v_fmac_f32_e32 v71, v72, v71
	v_div_scale_f32 v72, vcc, 1.0, v68, 1.0
	v_mul_f32_e32 v73, v72, v71
	v_fma_f32 v74, -v70, v73, v72
	v_fmac_f32_e32 v73, v74, v71
	v_fma_f32 v70, -v70, v73, v72
	v_div_fmas_f32 v70, v70, v71, v73
	v_div_fixup_f32 v68, v70, v68, 1.0
	v_pk_fma_f32 v[158:159], v[52:53], v[68:69], v[158:159]
	s_waitcnt vmcnt(30)
; __device__ __forceinline__ float sigmoidf_(float x) { return 1.f / (1.f + __expf(-x)); }
; template <int NI, class LA, class LB, class EP>
; __device__ __forceinline__ void gemm_tile(int K, LA loadA, LB loadB, EP epi, char* smem) {
;     ...
; #pragma unroll
;   for (int mi = 0; mi < 2; ++mi)
; #pragma unroll
;     for (int ni = 0; ni < NI; ++ni)
; #pragma unroll
;       for (int r = 0; r < 16; ++r) {
;         const int row = wm * 64 + mi * 32 + (r & 3) + 8 * (r >> 2) + 4 * (lane >> 5);
;         const int col = wn * (NI * 32) + ni * 32 + (lane & 31);
;         epi(mi, ni, r, row, col, acc[mi][ni][r]);
; __device__ __forceinline__ void phase_merge(const KP& p, char* smem, int* q, int xcc) {
;     ...
;           [&](int mi, int ni, int r, int row, int col, float v) {
;             const float gz = (float)G[(size_t)row * NU + col];
;             tot[mi][ni][r] += sigmoidf_(gz) * v;
;           },
	v_cvt_f32_f16_e32 v68, v196
	v_cvt_f32_f16_e32 v69, v197
	v_add_u32_e32 v96, 0x91000, v94
	global_load_ushort v196, v96, s[40:41]
	v_add_u32_e32 v96, 0x94a00, v94
	global_load_ushort v197, v96, s[40:41]
	v_mul_f32_e32 v68, 0xbfb8aa3b, v68
	v_mul_f32_e32 v69, 0xbfb8aa3b, v69
	v_exp_f32_e32 v68, v68
	v_exp_f32_e32 v69, v69
	s_nop 0
	v_pk_add_f32 v[68:69], v[68:69], 1.0 op_sel_hi:[1,0]
	s_nop 0
	v_div_scale_f32 v70, s[2:3], v69, v69, 1.0
	v_rcp_f32_e32 v71, v70
	s_nop 0
	v_fma_f32 v72, -v70, v71, 1.0
	v_fmac_f32_e32 v71, v72, v71
	v_div_scale_f32 v72, vcc, 1.0, v69, 1.0
	v_mul_f32_e32 v73, v72, v71
	v_fma_f32 v74, -v70, v73, v72
	v_fmac_f32_e32 v73, v74, v71
	v_fma_f32 v70, -v70, v73, v72
	v_div_fmas_f32 v70, v70, v71, v73
	v_div_fixup_f32 v69, v70, v69, 1.0
	v_div_scale_f32 v70, s[2:3], v68, v68, 1.0
	v_rcp_f32_e32 v71, v70
	s_nop 0
	v_fma_f32 v72, -v70, v71, 1.0
	v_fmac_f32_e32 v71, v72, v71
	v_div_scale_f32 v72, vcc, 1.0, v68, 1.0
	v_mul_f32_e32 v73, v72, v71
	v_fma_f32 v74, -v70, v73, v72
	v_fmac_f32_e32 v73, v74, v71
	v_fma_f32 v70, -v70, v73, v72
	v_div_fmas_f32 v70, v70, v71, v73
	v_div_fixup_f32 v68, v70, v68, 1.0
	v_pk_fma_f32 v[156:157], v[54:55], v[68:69], v[156:157]
	s_waitcnt vmcnt(30)
	v_cvt_f32_f16_e32 v68, v198
	v_cvt_f32_f16_e32 v69, v199
	v_add_u32_e32 v96, 0x98400, v94
	global_load_ushort v198, v96, s[40:41]
	v_add_u32_e32 v96, 0x9be00, v94
	global_load_ushort v199, v96, s[40:41]
	v_mul_f32_e32 v68, 0xbfb8aa3b, v68
	v_mul_f32_e32 v69, 0xbfb8aa3b, v69
	v_exp_f32_e32 v68, v68
	v_exp_f32_e32 v69, v69
	s_nop 0
	v_pk_add_f32 v[68:69], v[68:69], 1.0 op_sel_hi:[1,0]
	s_nop 0
	v_div_scale_f32 v70, s[2:3], v69, v69, 1.0
	v_rcp_f32_e32 v71, v70
	s_nop 0
	v_fma_f32 v72, -v70, v71, 1.0
	v_fmac_f32_e32 v71, v72, v71
	v_div_scale_f32 v72, vcc, 1.0, v69, 1.0
	v_mul_f32_e32 v73, v72, v71
	v_fma_f32 v74, -v70, v73, v72
	v_fmac_f32_e32 v73, v74, v71
	v_fma_f32 v70, -v70, v73, v72
	v_div_fmas_f32 v70, v70, v71, v73
	v_div_fixup_f32 v69, v70, v69, 1.0
	v_div_scale_f32 v70, s[2:3], v68, v68, 1.0
	v_rcp_f32_e32 v71, v70
	s_nop 0
	v_fma_f32 v72, -v70, v71, 1.0
	v_fmac_f32_e32 v71, v72, v71
	v_div_scale_f32 v72, vcc, 1.0, v68, 1.0
	v_mul_f32_e32 v73, v72, v71
	v_fma_f32 v74, -v70, v73, v72
	v_fmac_f32_e32 v73, v74, v71
	v_fma_f32 v70, -v70, v73, v72
	v_div_fmas_f32 v70, v70, v71, v73
	v_div_fixup_f32 v68, v70, v68, 1.0
	v_pk_fma_f32 v[154:155], v[56:57], v[68:69], v[154:155]
	s_waitcnt vmcnt(30)
	v_cvt_f32_f16_e32 v68, v200
	v_cvt_f32_f16_e32 v69, v201
	v_add_u32_e32 v96, 0xae000, v94
	global_load_ushort v200, v96, s[40:41]
	v_add_u32_e32 v96, 0xb1a00, v94
	global_load_ushort v201, v96, s[40:41]
	v_mul_f32_e32 v68, 0xbfb8aa3b, v68
	v_mul_f32_e32 v69, 0xbfb8aa3b, v69
	v_exp_f32_e32 v68, v68
	v_exp_f32_e32 v69, v69
	s_nop 0
	v_pk_add_f32 v[68:69], v[68:69], 1.0 op_sel_hi:[1,0]
	s_nop 0
	v_div_scale_f32 v70, s[2:3], v69, v69, 1.0
	v_rcp_f32_e32 v71, v70
	s_nop 0
	v_fma_f32 v72, -v70, v71, 1.0
	v_fmac_f32_e32 v71, v72, v71
	v_div_scale_f32 v72, vcc, 1.0, v69, 1.0
	v_mul_f32_e32 v73, v72, v71
	v_fma_f32 v74, -v70, v73, v72
	v_fmac_f32_e32 v73, v74, v71
	v_fma_f32 v70, -v70, v73, v72
	v_div_fmas_f32 v70, v70, v71, v73
	v_div_fixup_f32 v69, v70, v69, 1.0
	v_div_scale_f32 v70, s[2:3], v68, v68, 1.0
	v_rcp_f32_e32 v71, v70
	s_nop 0
	v_fma_f32 v72, -v70, v71, 1.0
	v_fmac_f32_e32 v71, v72, v71
	v_div_scale_f32 v72, vcc, 1.0, v68, 1.0
	v_mul_f32_e32 v73, v72, v71
	v_fma_f32 v74, -v70, v73, v72
	v_fmac_f32_e32 v73, v74, v71
	v_fma_f32 v70, -v70, v73, v72
	v_div_fmas_f32 v70, v70, v71, v73
	v_div_fixup_f32 v68, v70, v68, 1.0
	v_pk_fma_f32 v[152:153], v[58:59], v[68:69], v[152:153]
	s_waitcnt vmcnt(30)
	v_cvt_f32_f16_e32 v68, v202
	v_cvt_f32_f16_e32 v69, v203
	v_add_u32_e32 v96, 0xb5400, v94
	global_load_ushort v202, v96, s[40:41]
	v_add_u32_e32 v96, 0xb8e00, v94
	global_load_ushort v203, v96, s[40:41]
	v_mul_f32_e32 v68, 0xbfb8aa3b, v68
	v_mul_f32_e32 v69, 0xbfb8aa3b, v69
	v_exp_f32_e32 v68, v68
	v_exp_f32_e32 v69, v69
	s_nop 0
	v_pk_add_f32 v[68:69], v[68:69], 1.0 op_sel_hi:[1,0]
	s_nop 0
	v_div_scale_f32 v70, s[2:3], v69, v69, 1.0
	v_rcp_f32_e32 v71, v70
	s_nop 0
	v_fma_f32 v72, -v70, v71, 1.0
	v_fmac_f32_e32 v71, v72, v71
	v_div_scale_f32 v72, vcc, 1.0, v69, 1.0
	v_mul_f32_e32 v73, v72, v71
	v_fma_f32 v74, -v70, v73, v72
	v_fmac_f32_e32 v73, v74, v71
	v_fma_f32 v70, -v70, v73, v72
	v_div_fmas_f32 v70, v70, v71, v73
	v_div_fixup_f32 v69, v70, v69, 1.0
	v_div_scale_f32 v70, s[2:3], v68, v68, 1.0
	v_rcp_f32_e32 v71, v70
	s_nop 0
	v_fma_f32 v72, -v70, v71, 1.0
	v_fmac_f32_e32 v71, v72, v71
	v_div_scale_f32 v72, vcc, 1.0, v68, 1.0
	v_mul_f32_e32 v73, v72, v71
	v_fma_f32 v74, -v70, v73, v72
	v_fmac_f32_e32 v73, v74, v71
	v_fma_f32 v70, -v70, v73, v72
	v_div_fmas_f32 v70, v70, v71, v73
	v_div_fixup_f32 v68, v70, v68, 1.0
	v_pk_fma_f32 v[150:151], v[60:61], v[68:69], v[150:151]
	s_waitcnt vmcnt(30)
	v_cvt_f32_f16_e32 v68, v204
	v_cvt_f32_f16_e32 v69, v205
	v_add_u32_e32 v96, 0xcb000, v94
	global_load_ushort v204, v96, s[40:41]
	v_add_u32_e32 v96, 0xcea00, v94
	global_load_ushort v205, v96, s[40:41]
	v_mul_f32_e32 v68, 0xbfb8aa3b, v68
	v_mul_f32_e32 v69, 0xbfb8aa3b, v69
	v_exp_f32_e32 v68, v68
	v_exp_f32_e32 v69, v69
	s_nop 0
	v_pk_add_f32 v[68:69], v[68:69], 1.0 op_sel_hi:[1,0]
	s_nop 0
	v_div_scale_f32 v70, s[2:3], v69, v69, 1.0
	v_rcp_f32_e32 v71, v70
	s_nop 0
	v_fma_f32 v72, -v70, v71, 1.0
	v_fmac_f32_e32 v71, v72, v71
	v_div_scale_f32 v72, vcc, 1.0, v69, 1.0
	v_mul_f32_e32 v73, v72, v71
	v_fma_f32 v74, -v70, v73, v72
	v_fmac_f32_e32 v73, v74, v71
	v_fma_f32 v70, -v70, v73, v72
	v_div_fmas_f32 v70, v70, v71, v73
	v_div_fixup_f32 v69, v70, v69, 1.0
	v_div_scale_f32 v70, s[2:3], v68, v68, 1.0
	v_rcp_f32_e32 v71, v70
	s_nop 0
	v_fma_f32 v72, -v70, v71, 1.0
	v_fmac_f32_e32 v71, v72, v71
	v_div_scale_f32 v72, vcc, 1.0, v68, 1.0
	v_mul_f32_e32 v73, v72, v71
	v_fma_f32 v74, -v70, v73, v72
	v_fmac_f32_e32 v73, v74, v71
	v_fma_f32 v70, -v70, v73, v72
	v_div_fmas_f32 v70, v70, v71, v73
	v_div_fixup_f32 v68, v70, v68, 1.0
	v_pk_fma_f32 v[148:149], v[62:63], v[68:69], v[148:149]
	s_waitcnt vmcnt(30)
; __device__ __forceinline__ float sigmoidf_(float x) { return 1.f / (1.f + __expf(-x)); }
; template <int NI, class LA, class LB, class EP>
; __device__ __forceinline__ void gemm_tile(int K, LA loadA, LB loadB, EP epi, char* smem) {
;     ...
; #pragma unroll
;   for (int mi = 0; mi < 2; ++mi)
; #pragma unroll
;     for (int ni = 0; ni < NI; ++ni)
; #pragma unroll
;       for (int r = 0; r < 16; ++r) {
;         const int row = wm * 64 + mi * 32 + (r & 3) + 8 * (r >> 2) + 4 * (lane >> 5);
;         const int col = wn * (NI * 32) + ni * 32 + (lane & 31);
;         epi(mi, ni, r, row, col, acc[mi][ni][r]);
; __device__ __forceinline__ void phase_merge(const KP& p, char* smem, int* q, int xcc) {
;     ...
;           [&](int mi, int ni, int r, int row, int col, float v) {
;             const float gz = (float)G[(size_t)row * NU + col];
;             tot[mi][ni][r] += sigmoidf_(gz) * v;
;           },
	v_cvt_f32_f16_e32 v68, v206
	v_cvt_f32_f16_e32 v69, v207
	v_add_u32_e32 v96, 0xd2400, v94
	global_load_ushort v206, v96, s[40:41]
	v_add_u32_e32 v96, 0xd5e00, v94
	global_load_ushort v207, v96, s[40:41]
	v_mul_f32_e32 v68, 0xbfb8aa3b, v68
	v_mul_f32_e32 v69, 0xbfb8aa3b, v69
	v_exp_f32_e32 v68, v68
	v_exp_f32_e32 v69, v69
	s_nop 0
	v_pk_add_f32 v[68:69], v[68:69], 1.0 op_sel_hi:[1,0]
	s_nop 0
	v_div_scale_f32 v70, s[2:3], v69, v69, 1.0
	v_rcp_f32_e32 v71, v70
	s_nop 0
	v_fma_f32 v72, -v70, v71, 1.0
	v_fmac_f32_e32 v71, v72, v71
	v_div_scale_f32 v72, vcc, 1.0, v69, 1.0
	v_mul_f32_e32 v73, v72, v71
	v_fma_f32 v74, -v70, v73, v72
	v_fmac_f32_e32 v73, v74, v71
	v_fma_f32 v70, -v70, v73, v72
	v_div_fmas_f32 v70, v70, v71, v73
	v_div_fixup_f32 v69, v70, v69, 1.0
	v_div_scale_f32 v70, s[2:3], v68, v68, 1.0
	v_rcp_f32_e32 v71, v70
	s_nop 0
	v_fma_f32 v72, -v70, v71, 1.0
	v_fmac_f32_e32 v71, v72, v71
	v_div_scale_f32 v72, vcc, 1.0, v68, 1.0
	v_mul_f32_e32 v73, v72, v71
	v_fma_f32 v74, -v70, v73, v72
	v_fmac_f32_e32 v73, v74, v71
	v_fma_f32 v70, -v70, v73, v72
	v_div_fmas_f32 v70, v70, v71, v73
	v_div_fixup_f32 v68, v70, v68, 1.0
	v_pk_fma_f32 v[146:147], v[64:65], v[68:69], v[146:147]
	s_waitcnt vmcnt(30)
	v_cvt_f32_f16_e32 v68, v208
	v_cvt_f32_f16_e32 v69, v209
	v_add_u32_e32 v96, 0x74000, v94
	global_load_ushort v208, v96, s[40:41] offset:64
	v_add_u32_e32 v96, 0x77a00, v94
	global_load_ushort v209, v96, s[40:41] offset:64
	v_mul_f32_e32 v68, 0xbfb8aa3b, v68
	v_mul_f32_e32 v69, 0xbfb8aa3b, v69
	v_exp_f32_e32 v68, v68
	v_exp_f32_e32 v69, v69
	s_nop 0
	v_pk_add_f32 v[68:69], v[68:69], 1.0 op_sel_hi:[1,0]
	s_nop 0
	v_div_scale_f32 v70, s[2:3], v69, v69, 1.0
	v_rcp_f32_e32 v71, v70
	s_nop 0
	v_fma_f32 v72, -v70, v71, 1.0
	v_fmac_f32_e32 v71, v72, v71
	v_div_scale_f32 v72, vcc, 1.0, v69, 1.0
	v_mul_f32_e32 v73, v72, v71
	v_fma_f32 v74, -v70, v73, v72
	v_fmac_f32_e32 v73, v74, v71
	v_fma_f32 v70, -v70, v73, v72
	v_div_fmas_f32 v70, v70, v71, v73
	v_div_fixup_f32 v69, v70, v69, 1.0
	v_div_scale_f32 v70, s[2:3], v68, v68, 1.0
	v_rcp_f32_e32 v71, v70
	s_nop 0
	v_fma_f32 v72, -v70, v71, 1.0
	v_fmac_f32_e32 v71, v72, v71
	v_div_scale_f32 v72, vcc, 1.0, v68, 1.0
	v_mul_f32_e32 v73, v72, v71
	v_fma_f32 v74, -v70, v73, v72
	v_fmac_f32_e32 v73, v74, v71
	v_fma_f32 v70, -v70, v73, v72
	v_div_fmas_f32 v70, v70, v71, v73
	v_div_fixup_f32 v68, v70, v68, 1.0
	v_pk_fma_f32 v[144:145], v[34:35], v[68:69], v[144:145]
	s_waitcnt vmcnt(30)
	v_cvt_f32_f16_e32 v68, v210
	v_cvt_f32_f16_e32 v69, v211
	v_add_u32_e32 v96, 0x7b400, v94
	global_load_ushort v210, v96, s[40:41] offset:64
	v_add_u32_e32 v96, 0x7ee00, v94
	global_load_ushort v211, v96, s[40:41] offset:64
	v_mul_f32_e32 v68, 0xbfb8aa3b, v68
	v_mul_f32_e32 v69, 0xbfb8aa3b, v69
	v_exp_f32_e32 v68, v68
	v_exp_f32_e32 v69, v69
	s_nop 0
	v_pk_add_f32 v[68:69], v[68:69], 1.0 op_sel_hi:[1,0]
	s_nop 0
	v_div_scale_f32 v70, s[2:3], v69, v69, 1.0
	v_rcp_f32_e32 v71, v70
	s_nop 0
	v_fma_f32 v72, -v70, v71, 1.0
	v_fmac_f32_e32 v71, v72, v71
	v_div_scale_f32 v72, vcc, 1.0, v69, 1.0
	v_mul_f32_e32 v73, v72, v71
	v_fma_f32 v74, -v70, v73, v72
	v_fmac_f32_e32 v73, v74, v71
	v_fma_f32 v70, -v70, v73, v72
	v_div_fmas_f32 v70, v70, v71, v73
	v_div_fixup_f32 v69, v70, v69, 1.0
	v_div_scale_f32 v70, s[2:3], v68, v68, 1.0
	v_rcp_f32_e32 v71, v70
	s_nop 0
	v_fma_f32 v72, -v70, v71, 1.0
	v_fmac_f32_e32 v71, v72, v71
	v_div_scale_f32 v72, vcc, 1.0, v68, 1.0
	v_mul_f32_e32 v73, v72, v71
	v_fma_f32 v74, -v70, v73, v72
	v_fmac_f32_e32 v73, v74, v71
	v_fma_f32 v70, -v70, v73, v72
	v_div_fmas_f32 v70, v70, v71, v73
	v_div_fixup_f32 v68, v70, v68, 1.0
	v_pk_fma_f32 v[142:143], v[36:37], v[68:69], v[142:143]
	s_waitcnt vmcnt(30)
	v_cvt_f32_f16_e32 v68, v212
	v_cvt_f32_f16_e32 v69, v213
	v_add_u32_e32 v96, 0x91000, v94
	global_load_ushort v212, v96, s[40:41] offset:64
	v_add_u32_e32 v96, 0x94a00, v94
	global_load_ushort v213, v96, s[40:41] offset:64
	v_mul_f32_e32 v68, 0xbfb8aa3b, v68
	v_mul_f32_e32 v69, 0xbfb8aa3b, v69
	v_exp_f32_e32 v68, v68
	v_exp_f32_e32 v69, v69
	s_nop 0
	v_pk_add_f32 v[68:69], v[68:69], 1.0 op_sel_hi:[1,0]
	s_nop 0
	v_div_scale_f32 v70, s[2:3], v69, v69, 1.0
	v_rcp_f32_e32 v71, v70
	s_nop 0
	v_fma_f32 v72, -v70, v71, 1.0
	v_fmac_f32_e32 v71, v72, v71
	v_div_scale_f32 v72, vcc, 1.0, v69, 1.0
	v_mul_f32_e32 v73, v72, v71
	v_fma_f32 v74, -v70, v73, v72
	v_fmac_f32_e32 v73, v74, v71
	v_fma_f32 v70, -v70, v73, v72
	v_div_fmas_f32 v70, v70, v71, v73
	v_div_fixup_f32 v69, v70, v69, 1.0
	v_div_scale_f32 v70, s[2:3], v68, v68, 1.0
	v_rcp_f32_e32 v71, v70
	s_nop 0
	v_fma_f32 v72, -v70, v71, 1.0
	v_fmac_f32_e32 v71, v72, v71
	v_div_scale_f32 v72, vcc, 1.0, v68, 1.0
	v_mul_f32_e32 v73, v72, v71
	v_fma_f32 v74, -v70, v73, v72
	v_fmac_f32_e32 v73, v74, v71
	v_fma_f32 v70, -v70, v73, v72
	v_div_fmas_f32 v70, v70, v71, v73
	v_div_fixup_f32 v68, v70, v68, 1.0
	v_pk_fma_f32 v[140:141], v[38:39], v[68:69], v[140:141]
	s_waitcnt vmcnt(30)
	v_cvt_f32_f16_e32 v68, v214
	v_cvt_f32_f16_e32 v69, v215
	v_add_u32_e32 v96, 0x98400, v94
	global_load_ushort v214, v96, s[40:41] offset:64
	v_add_u32_e32 v96, 0x9be00, v94
	global_load_ushort v215, v96, s[40:41] offset:64
	v_mul_f32_e32 v68, 0xbfb8aa3b, v68
	v_mul_f32_e32 v69, 0xbfb8aa3b, v69
	v_exp_f32_e32 v68, v68
	v_exp_f32_e32 v69, v69
	s_nop 0
	v_pk_add_f32 v[68:69], v[68:69], 1.0 op_sel_hi:[1,0]
	s_nop 0
	v_div_scale_f32 v70, s[2:3], v69, v69, 1.0
	v_rcp_f32_e32 v71, v70
	s_nop 0
	v_fma_f32 v72, -v70, v71, 1.0
	v_fmac_f32_e32 v71, v72, v71
	v_div_scale_f32 v72, vcc, 1.0, v69, 1.0
	v_mul_f32_e32 v73, v72, v71
	v_fma_f32 v74, -v70, v73, v72
	v_fmac_f32_e32 v73, v74, v71
	v_fma_f32 v70, -v70, v73, v72
	v_div_fmas_f32 v70, v70, v71, v73
	v_div_fixup_f32 v69, v70, v69, 1.0
	v_div_scale_f32 v70, s[2:3], v68, v68, 1.0
	v_rcp_f32_e32 v71, v70
	s_nop 0
	v_fma_f32 v72, -v70, v71, 1.0
	v_fmac_f32_e32 v71, v72, v71
	v_div_scale_f32 v72, vcc, 1.0, v68, 1.0
	v_mul_f32_e32 v73, v72, v71
	v_fma_f32 v74, -v70, v73, v72
	v_fmac_f32_e32 v73, v74, v71
	v_fma_f32 v70, -v70, v73, v72
	v_div_fmas_f32 v70, v70, v71, v73
	v_div_fixup_f32 v68, v70, v68, 1.0
	v_pk_fma_f32 v[138:139], v[40:41], v[68:69], v[138:139]
	s_waitcnt vmcnt(30)
; __device__ __forceinline__ float sigmoidf_(float x) { return 1.f / (1.f + __expf(-x)); }
; template <int NI, class LA, class LB, class EP>
; __device__ __forceinline__ void gemm_tile(int K, LA loadA, LB loadB, EP epi, char* smem) {
;     ...
; #pragma unroll
;   for (int mi = 0; mi < 2; ++mi)
; #pragma unroll
;     for (int ni = 0; ni < NI; ++ni)
; #pragma unroll
;       for (int r = 0; r < 16; ++r) {
;         const int row = wm * 64 + mi * 32 + (r & 3) + 8 * (r >> 2) + 4 * (lane >> 5);
;         const int col = wn * (NI * 32) + ni * 32 + (lane & 31);
;         epi(mi, ni, r, row, col, acc[mi][ni][r]);
; __device__ __forceinline__ void phase_merge(const KP& p, char* smem, int* q, int xcc) {
;     ...
;           [&](int mi, int ni, int r, int row, int col, float v) {
;             const float gz = (float)G[(size_t)row * NU + col];
;             tot[mi][ni][r] += sigmoidf_(gz) * v;
;           },
	v_cvt_f32_f16_e32 v68, v216
	v_cvt_f32_f16_e32 v69, v217
	v_add_u32_e32 v96, 0xae000, v94
	global_load_ushort v216, v96, s[40:41] offset:64
	v_add_u32_e32 v96, 0xb1a00, v94
	global_load_ushort v217, v96, s[40:41] offset:64
	v_mul_f32_e32 v68, 0xbfb8aa3b, v68
	v_mul_f32_e32 v69, 0xbfb8aa3b, v69
	v_exp_f32_e32 v68, v68
	v_exp_f32_e32 v69, v69
	s_nop 0
	v_pk_add_f32 v[68:69], v[68:69], 1.0 op_sel_hi:[1,0]
	s_nop 0
	v_div_scale_f32 v70, s[2:3], v69, v69, 1.0
	v_rcp_f32_e32 v71, v70
	s_nop 0
	v_fma_f32 v72, -v70, v71, 1.0
	v_fmac_f32_e32 v71, v72, v71
	v_div_scale_f32 v72, vcc, 1.0, v69, 1.0
	v_mul_f32_e32 v73, v72, v71
	v_fma_f32 v74, -v70, v73, v72
	v_fmac_f32_e32 v73, v74, v71
	v_fma_f32 v70, -v70, v73, v72
	v_div_fmas_f32 v70, v70, v71, v73
	v_div_fixup_f32 v69, v70, v69, 1.0
	v_div_scale_f32 v70, s[2:3], v68, v68, 1.0
	v_rcp_f32_e32 v71, v70
	s_nop 0
	v_fma_f32 v72, -v70, v71, 1.0
	v_fmac_f32_e32 v71, v72, v71
	v_div_scale_f32 v72, vcc, 1.0, v68, 1.0
	v_mul_f32_e32 v73, v72, v71
	v_fma_f32 v74, -v70, v73, v72
	v_fmac_f32_e32 v73, v74, v71
	v_fma_f32 v70, -v70, v73, v72
	v_div_fmas_f32 v70, v70, v71, v73
	v_div_fixup_f32 v68, v70, v68, 1.0
	v_pk_fma_f32 v[136:137], v[42:43], v[68:69], v[136:137]
	s_waitcnt vmcnt(30)
	v_cvt_f32_f16_e32 v68, v218
	v_cvt_f32_f16_e32 v69, v219
	v_add_u32_e32 v96, 0xb5400, v94
	global_load_ushort v218, v96, s[40:41] offset:64
	v_add_u32_e32 v96, 0xb8e00, v94
	global_load_ushort v219, v96, s[40:41] offset:64
	v_mul_f32_e32 v68, 0xbfb8aa3b, v68
	v_mul_f32_e32 v69, 0xbfb8aa3b, v69
	v_exp_f32_e32 v68, v68
	v_exp_f32_e32 v69, v69
	s_nop 0
	v_pk_add_f32 v[68:69], v[68:69], 1.0 op_sel_hi:[1,0]
	s_nop 0
	v_div_scale_f32 v70, s[2:3], v69, v69, 1.0
	v_rcp_f32_e32 v71, v70
	s_nop 0
	v_fma_f32 v72, -v70, v71, 1.0
	v_fmac_f32_e32 v71, v72, v71
	v_div_scale_f32 v72, vcc, 1.0, v69, 1.0
	v_mul_f32_e32 v73, v72, v71
	v_fma_f32 v74, -v70, v73, v72
	v_fmac_f32_e32 v73, v74, v71
	v_fma_f32 v70, -v70, v73, v72
	v_div_fmas_f32 v70, v70, v71, v73
	v_div_fixup_f32 v69, v70, v69, 1.0
	v_div_scale_f32 v70, s[2:3], v68, v68, 1.0
	v_rcp_f32_e32 v71, v70
	s_nop 0
	v_fma_f32 v72, -v70, v71, 1.0
	v_fmac_f32_e32 v71, v72, v71
	v_div_scale_f32 v72, vcc, 1.0, v68, 1.0
	v_mul_f32_e32 v73, v72, v71
	v_fma_f32 v74, -v70, v73, v72
	v_fmac_f32_e32 v73, v74, v71
	v_fma_f32 v70, -v70, v73, v72
	v_div_fmas_f32 v70, v70, v71, v73
	v_div_fixup_f32 v68, v70, v68, 1.0
	v_pk_fma_f32 v[134:135], v[44:45], v[68:69], v[134:135]
	s_waitcnt vmcnt(30)
	v_cvt_f32_f16_e32 v68, v220
	v_cvt_f32_f16_e32 v69, v221
	v_add_u32_e32 v96, 0xcb000, v94
	global_load_ushort v220, v96, s[40:41] offset:64
	v_add_u32_e32 v96, 0xcea00, v94
	global_load_ushort v221, v96, s[40:41] offset:64
	v_mul_f32_e32 v68, 0xbfb8aa3b, v68
	v_mul_f32_e32 v69, 0xbfb8aa3b, v69
	v_exp_f32_e32 v68, v68
	v_exp_f32_e32 v69, v69
	s_nop 0
	v_pk_add_f32 v[68:69], v[68:69], 1.0 op_sel_hi:[1,0]
	s_nop 0
	v_div_scale_f32 v70, s[2:3], v69, v69, 1.0
	v_rcp_f32_e32 v71, v70
	s_nop 0
	v_fma_f32 v72, -v70, v71, 1.0
	v_fmac_f32_e32 v71, v72, v71
	v_div_scale_f32 v72, vcc, 1.0, v69, 1.0
	v_mul_f32_e32 v73, v72, v71
	v_fma_f32 v74, -v70, v73, v72
	v_fmac_f32_e32 v73, v74, v71
	v_fma_f32 v70, -v70, v73, v72
	v_div_fmas_f32 v70, v70, v71, v73
	v_div_fixup_f32 v69, v70, v69, 1.0
	v_div_scale_f32 v70, s[2:3], v68, v68, 1.0
	v_rcp_f32_e32 v71, v70
	s_nop 0
	v_fma_f32 v72, -v70, v71, 1.0
	v_fmac_f32_e32 v71, v72, v71
	v_div_scale_f32 v72, vcc, 1.0, v68, 1.0
	v_mul_f32_e32 v73, v72, v71
	v_fma_f32 v74, -v70, v73, v72
	v_fmac_f32_e32 v73, v74, v71
	v_fma_f32 v70, -v70, v73, v72
	v_div_fmas_f32 v70, v70, v71, v73
	v_div_fixup_f32 v68, v70, v68, 1.0
	v_pk_fma_f32 v[132:133], v[46:47], v[68:69], v[132:133]
	s_waitcnt vmcnt(30)
	v_cvt_f32_f16_e32 v68, v222
	v_cvt_f32_f16_e32 v69, v223
	v_add_u32_e32 v96, 0xd2400, v94
	global_load_ushort v222, v96, s[40:41] offset:64
	v_add_u32_e32 v96, 0xd5e00, v94
	global_load_ushort v223, v96, s[40:41] offset:64
	v_mul_f32_e32 v68, 0xbfb8aa3b, v68
	v_mul_f32_e32 v69, 0xbfb8aa3b, v69
	v_exp_f32_e32 v68, v68
	v_exp_f32_e32 v69, v69
	s_nop 0
	v_pk_add_f32 v[68:69], v[68:69], 1.0 op_sel_hi:[1,0]
	s_nop 0
	v_div_scale_f32 v70, s[2:3], v69, v69, 1.0
	v_rcp_f32_e32 v71, v70
	s_nop 0
	v_fma_f32 v72, -v70, v71, 1.0
	v_fmac_f32_e32 v71, v72, v71
	v_div_scale_f32 v72, vcc, 1.0, v69, 1.0
	v_mul_f32_e32 v73, v72, v71
	v_fma_f32 v74, -v70, v73, v72
	v_fmac_f32_e32 v73, v74, v71
	v_fma_f32 v70, -v70, v73, v72
	v_div_fmas_f32 v70, v70, v71, v73
	v_div_fixup_f32 v69, v70, v69, 1.0
	v_div_scale_f32 v70, s[2:3], v68, v68, 1.0
	v_rcp_f32_e32 v71, v70
	s_nop 0
	v_fma_f32 v72, -v70, v71, 1.0
	v_fmac_f32_e32 v71, v72, v71
	v_div_scale_f32 v72, vcc, 1.0, v68, 1.0
	v_mul_f32_e32 v73, v72, v71
	v_fma_f32 v74, -v70, v73, v72
	v_fmac_f32_e32 v73, v74, v71
	v_fma_f32 v70, -v70, v73, v72
	v_div_fmas_f32 v70, v70, v71, v73
	v_div_fixup_f32 v68, v70, v68, 1.0
	v_pk_fma_f32 v[130:131], v[48:49], v[68:69], v[130:131]
	s_waitcnt vmcnt(30)
	v_cvt_f32_f16_e32 v68, v192
	v_cvt_f32_f16_e32 v69, v193
	v_mul_f32_e32 v68, 0xbfb8aa3b, v68
	v_mul_f32_e32 v69, 0xbfb8aa3b, v69
	v_exp_f32_e32 v68, v68
	v_exp_f32_e32 v69, v69
	s_nop 0
	v_pk_add_f32 v[68:69], v[68:69], 1.0 op_sel_hi:[1,0]
	s_nop 0
	v_div_scale_f32 v70, s[2:3], v69, v69, 1.0
	v_rcp_f32_e32 v71, v70
	s_nop 0
	v_fma_f32 v72, -v70, v71, 1.0
	v_fmac_f32_e32 v71, v72, v71
	v_div_scale_f32 v72, vcc, 1.0, v69, 1.0
	v_mul_f32_e32 v73, v72, v71
	v_fma_f32 v74, -v70, v73, v72
	v_fmac_f32_e32 v73, v74, v71
	v_fma_f32 v70, -v70, v73, v72
	v_div_fmas_f32 v70, v70, v71, v73
	v_div_fixup_f32 v69, v70, v69, 1.0
	v_div_scale_f32 v70, s[2:3], v68, v68, 1.0
	v_rcp_f32_e32 v71, v70
	s_nop 0
	v_fma_f32 v72, -v70, v71, 1.0
	v_fmac_f32_e32 v71, v72, v71
	v_div_scale_f32 v72, vcc, 1.0, v68, 1.0
	v_mul_f32_e32 v73, v72, v71
	v_fma_f32 v74, -v70, v73, v72
	v_fmac_f32_e32 v73, v74, v71
	v_fma_f32 v70, -v70, v73, v72
	v_div_fmas_f32 v70, v70, v71, v73
	v_div_fixup_f32 v68, v70, v68, 1.0
	v_pk_fma_f32 v[128:129], v[18:19], v[68:69], v[128:129]
	s_waitcnt vmcnt(28)
; __device__ __forceinline__ float sigmoidf_(float x) { return 1.f / (1.f + __expf(-x)); }
; template <int NI, class LA, class LB, class EP>
; __device__ __forceinline__ void gemm_tile(int K, LA loadA, LB loadB, EP epi, char* smem) {
;     ...
; #pragma unroll
;   for (int mi = 0; mi < 2; ++mi)
; #pragma unroll
;     for (int ni = 0; ni < NI; ++ni)
; #pragma unroll
;       for (int r = 0; r < 16; ++r) {
;         const int row = wm * 64 + mi * 32 + (r & 3) + 8 * (r >> 2) + 4 * (lane >> 5);
;         const int col = wn * (NI * 32) + ni * 32 + (lane & 31);
;         epi(mi, ni, r, row, col, acc[mi][ni][r]);
; __device__ __forceinline__ void phase_merge(const KP& p, char* smem, int* q, int xcc) {
;     ...
;           [&](int mi, int ni, int r, int row, int col, float v) {
;             const float gz = (float)G[(size_t)row * NU + col];
;             tot[mi][ni][r] += sigmoidf_(gz) * v;
;           },
	v_cvt_f32_f16_e32 v68, v194
	v_cvt_f32_f16_e32 v69, v195
	v_mul_f32_e32 v68, 0xbfb8aa3b, v68
	v_mul_f32_e32 v69, 0xbfb8aa3b, v69
	v_exp_f32_e32 v68, v68
	v_exp_f32_e32 v69, v69
	s_nop 0
	v_pk_add_f32 v[68:69], v[68:69], 1.0 op_sel_hi:[1,0]
	s_nop 0
	v_div_scale_f32 v70, s[2:3], v69, v69, 1.0
	v_rcp_f32_e32 v71, v70
	s_nop 0
	v_fma_f32 v72, -v70, v71, 1.0
	v_fmac_f32_e32 v71, v72, v71
	v_div_scale_f32 v72, vcc, 1.0, v69, 1.0
	v_mul_f32_e32 v73, v72, v71
	v_fma_f32 v74, -v70, v73, v72
	v_fmac_f32_e32 v73, v74, v71
	v_fma_f32 v70, -v70, v73, v72
	v_div_fmas_f32 v70, v70, v71, v73
	v_div_fixup_f32 v69, v70, v69, 1.0
	v_div_scale_f32 v70, s[2:3], v68, v68, 1.0
	v_rcp_f32_e32 v71, v70
	s_nop 0
	v_fma_f32 v72, -v70, v71, 1.0
	v_fmac_f32_e32 v71, v72, v71
	v_div_scale_f32 v72, vcc, 1.0, v68, 1.0
	v_mul_f32_e32 v73, v72, v71
	v_fma_f32 v74, -v70, v73, v72
	v_fmac_f32_e32 v73, v74, v71
	v_fma_f32 v70, -v70, v73, v72
	v_div_fmas_f32 v70, v70, v71, v73
	v_div_fixup_f32 v68, v70, v68, 1.0
	v_pk_fma_f32 v[126:127], v[20:21], v[68:69], v[126:127]
	s_waitcnt vmcnt(26)
	v_cvt_f32_f16_e32 v68, v196
	v_cvt_f32_f16_e32 v69, v197
	v_mul_f32_e32 v68, 0xbfb8aa3b, v68
	v_mul_f32_e32 v69, 0xbfb8aa3b, v69
	v_exp_f32_e32 v68, v68
	v_exp_f32_e32 v69, v69
	s_nop 0
	v_pk_add_f32 v[68:69], v[68:69], 1.0 op_sel_hi:[1,0]
	s_nop 0
	v_div_scale_f32 v70, s[2:3], v69, v69, 1.0
	v_rcp_f32_e32 v71, v70
	s_nop 0
	v_fma_f32 v72, -v70, v71, 1.0
	v_fmac_f32_e32 v71, v72, v71
	v_div_scale_f32 v72, vcc, 1.0, v69, 1.0
	v_mul_f32_e32 v73, v72, v71
	v_fma_f32 v74, -v70, v73, v72
	v_fmac_f32_e32 v73, v74, v71
	v_fma_f32 v70, -v70, v73, v72
	v_div_fmas_f32 v70, v70, v71, v73
	v_div_fixup_f32 v69, v70, v69, 1.0
	v_div_scale_f32 v70, s[2:3], v68, v68, 1.0
	v_rcp_f32_e32 v71, v70
	s_nop 0
	v_fma_f32 v72, -v70, v71, 1.0
	v_fmac_f32_e32 v71, v72, v71
	v_div_scale_f32 v72, vcc, 1.0, v68, 1.0
	v_mul_f32_e32 v73, v72, v71
	v_fma_f32 v74, -v70, v73, v72
	v_fmac_f32_e32 v73, v74, v71
	v_fma_f32 v70, -v70, v73, v72
	v_div_fmas_f32 v70, v70, v71, v73
	v_div_fixup_f32 v68, v70, v68, 1.0
	v_pk_fma_f32 v[124:125], v[22:23], v[68:69], v[124:125]
	s_waitcnt vmcnt(24)
	v_cvt_f32_f16_e32 v68, v198
	v_cvt_f32_f16_e32 v69, v199
	v_mul_f32_e32 v68, 0xbfb8aa3b, v68
	v_mul_f32_e32 v69, 0xbfb8aa3b, v69
	v_exp_f32_e32 v68, v68
	v_exp_f32_e32 v69, v69
	s_nop 0
	v_pk_add_f32 v[68:69], v[68:69], 1.0 op_sel_hi:[1,0]
	s_nop 0
	v_div_scale_f32 v70, s[2:3], v69, v69, 1.0
	v_rcp_f32_e32 v71, v70
	s_nop 0
	v_fma_f32 v72, -v70, v71, 1.0
	v_fmac_f32_e32 v71, v72, v71
	v_div_scale_f32 v72, vcc, 1.0, v69, 1.0
	v_mul_f32_e32 v73, v72, v71
	v_fma_f32 v74, -v70, v73, v72
	v_fmac_f32_e32 v73, v74, v71
	v_fma_f32 v70, -v70, v73, v72
	v_div_fmas_f32 v70, v70, v71, v73
	v_div_fixup_f32 v69, v70, v69, 1.0
	v_div_scale_f32 v70, s[2:3], v68, v68, 1.0
	v_rcp_f32_e32 v71, v70
	s_nop 0
	v_fma_f32 v72, -v70, v71, 1.0
	v_fmac_f32_e32 v71, v72, v71
	v_div_scale_f32 v72, vcc, 1.0, v68, 1.0
	v_mul_f32_e32 v73, v72, v71
	v_fma_f32 v74, -v70, v73, v72
	v_fmac_f32_e32 v73, v74, v71
	v_fma_f32 v70, -v70, v73, v72
	v_div_fmas_f32 v70, v70, v71, v73
	v_div_fixup_f32 v68, v70, v68, 1.0
	v_pk_fma_f32 v[122:123], v[24:25], v[68:69], v[122:123]
	s_waitcnt vmcnt(22)
	v_cvt_f32_f16_e32 v68, v200
	v_cvt_f32_f16_e32 v69, v201
	v_mul_f32_e32 v68, 0xbfb8aa3b, v68
	v_mul_f32_e32 v69, 0xbfb8aa3b, v69
	v_exp_f32_e32 v68, v68
	v_exp_f32_e32 v69, v69
	s_nop 0
	v_pk_add_f32 v[68:69], v[68:69], 1.0 op_sel_hi:[1,0]
	s_nop 0
	v_div_scale_f32 v70, s[2:3], v69, v69, 1.0
	v_rcp_f32_e32 v71, v70
	s_nop 0
	v_fma_f32 v72, -v70, v71, 1.0
	v_fmac_f32_e32 v71, v72, v71
	v_div_scale_f32 v72, vcc, 1.0, v69, 1.0
	v_mul_f32_e32 v73, v72, v71
	v_fma_f32 v74, -v70, v73, v72
	v_fmac_f32_e32 v73, v74, v71
	v_fma_f32 v70, -v70, v73, v72
	v_div_fmas_f32 v70, v70, v71, v73
	v_div_fixup_f32 v69, v70, v69, 1.0
	v_div_scale_f32 v70, s[2:3], v68, v68, 1.0
	v_rcp_f32_e32 v71, v70
	s_nop 0
	v_fma_f32 v72, -v70, v71, 1.0
	v_fmac_f32_e32 v71, v72, v71
	v_div_scale_f32 v72, vcc, 1.0, v68, 1.0
	v_mul_f32_e32 v73, v72, v71
	v_fma_f32 v74, -v70, v73, v72
	v_fmac_f32_e32 v73, v74, v71
	v_fma_f32 v70, -v70, v73, v72
	v_div_fmas_f32 v70, v70, v71, v73
	v_div_fixup_f32 v68, v70, v68, 1.0
	v_pk_fma_f32 v[120:121], v[26:27], v[68:69], v[120:121]
	s_waitcnt vmcnt(20)
	v_cvt_f32_f16_e32 v68, v202
	v_cvt_f32_f16_e32 v69, v203
	v_mul_f32_e32 v68, 0xbfb8aa3b, v68
	v_mul_f32_e32 v69, 0xbfb8aa3b, v69
	v_exp_f32_e32 v68, v68
	v_exp_f32_e32 v69, v69
	s_nop 0
	v_pk_add_f32 v[68:69], v[68:69], 1.0 op_sel_hi:[1,0]
	s_nop 0
	v_div_scale_f32 v70, s[2:3], v69, v69, 1.0
	v_rcp_f32_e32 v71, v70
	s_nop 0
	v_fma_f32 v72, -v70, v71, 1.0
	v_fmac_f32_e32 v71, v72, v71
	v_div_scale_f32 v72, vcc, 1.0, v69, 1.0
	v_mul_f32_e32 v73, v72, v71
	v_fma_f32 v74, -v70, v73, v72
	v_fmac_f32_e32 v73, v74, v71
	v_fma_f32 v70, -v70, v73, v72
	v_div_fmas_f32 v70, v70, v71, v73
	v_div_fixup_f32 v69, v70, v69, 1.0
	v_div_scale_f32 v70, s[2:3], v68, v68, 1.0
	v_rcp_f32_e32 v71, v70
	s_nop 0
	v_fma_f32 v72, -v70, v71, 1.0
	v_fmac_f32_e32 v71, v72, v71
	v_div_scale_f32 v72, vcc, 1.0, v68, 1.0
	v_mul_f32_e32 v73, v72, v71
	v_fma_f32 v74, -v70, v73, v72
	v_fmac_f32_e32 v73, v74, v71
	v_fma_f32 v70, -v70, v73, v72
	v_div_fmas_f32 v70, v70, v71, v73
	v_div_fixup_f32 v68, v70, v68, 1.0
	v_pk_fma_f32 v[118:119], v[28:29], v[68:69], v[118:119]
	s_waitcnt vmcnt(18)
; __device__ __forceinline__ float sigmoidf_(float x) { return 1.f / (1.f + __expf(-x)); }
; template <int NI, class LA, class LB, class EP>
; __device__ __forceinline__ void gemm_tile(int K, LA loadA, LB loadB, EP epi, char* smem) {
;     ...
; #pragma unroll
;   for (int mi = 0; mi < 2; ++mi)
; #pragma unroll
;     for (int ni = 0; ni < NI; ++ni)
; #pragma unroll
;       for (int r = 0; r < 16; ++r) {
;         const int row = wm * 64 + mi * 32 + (r & 3) + 8 * (r >> 2) + 4 * (lane >> 5);
;         const int col = wn * (NI * 32) + ni * 32 + (lane & 31);
;         epi(mi, ni, r, row, col, acc[mi][ni][r]);
; __device__ __forceinline__ void phase_merge(const KP& p, char* smem, int* q, int xcc) {
;     ...
;           [&](int mi, int ni, int r, int row, int col, float v) {
;             const float gz = (float)G[(size_t)row * NU + col];
;             tot[mi][ni][r] += sigmoidf_(gz) * v;
;           },
	v_cvt_f32_f16_e32 v68, v204
	v_cvt_f32_f16_e32 v69, v205
	v_mul_f32_e32 v68, 0xbfb8aa3b, v68
	v_mul_f32_e32 v69, 0xbfb8aa3b, v69
	v_exp_f32_e32 v68, v68
	v_exp_f32_e32 v69, v69
	s_nop 0
	v_pk_add_f32 v[68:69], v[68:69], 1.0 op_sel_hi:[1,0]
	s_nop 0
	v_div_scale_f32 v70, s[2:3], v69, v69, 1.0
	v_rcp_f32_e32 v71, v70
	s_nop 0
	v_fma_f32 v72, -v70, v71, 1.0
	v_fmac_f32_e32 v71, v72, v71
	v_div_scale_f32 v72, vcc, 1.0, v69, 1.0
	v_mul_f32_e32 v73, v72, v71
	v_fma_f32 v74, -v70, v73, v72
	v_fmac_f32_e32 v73, v74, v71
	v_fma_f32 v70, -v70, v73, v72
	v_div_fmas_f32 v70, v70, v71, v73
	v_div_fixup_f32 v69, v70, v69, 1.0
	v_div_scale_f32 v70, s[2:3], v68, v68, 1.0
	v_rcp_f32_e32 v71, v70
	s_nop 0
	v_fma_f32 v72, -v70, v71, 1.0
	v_fmac_f32_e32 v71, v72, v71
	v_div_scale_f32 v72, vcc, 1.0, v68, 1.0
	v_mul_f32_e32 v73, v72, v71
	v_fma_f32 v74, -v70, v73, v72
	v_fmac_f32_e32 v73, v74, v71
	v_fma_f32 v70, -v70, v73, v72
	v_div_fmas_f32 v70, v70, v71, v73
	v_div_fixup_f32 v68, v70, v68, 1.0
	v_pk_fma_f32 v[116:117], v[30:31], v[68:69], v[116:117]
	s_waitcnt vmcnt(16)
	v_cvt_f32_f16_e32 v68, v206
	v_cvt_f32_f16_e32 v69, v207
	v_mul_f32_e32 v68, 0xbfb8aa3b, v68
	v_mul_f32_e32 v69, 0xbfb8aa3b, v69
	v_exp_f32_e32 v68, v68
	v_exp_f32_e32 v69, v69
	s_nop 0
	v_pk_add_f32 v[68:69], v[68:69], 1.0 op_sel_hi:[1,0]
	s_nop 0
	v_div_scale_f32 v70, s[2:3], v69, v69, 1.0
	v_rcp_f32_e32 v71, v70
	s_nop 0
	v_fma_f32 v72, -v70, v71, 1.0
	v_fmac_f32_e32 v71, v72, v71
	v_div_scale_f32 v72, vcc, 1.0, v69, 1.0
	v_mul_f32_e32 v73, v72, v71
	v_fma_f32 v74, -v70, v73, v72
	v_fmac_f32_e32 v73, v74, v71
	v_fma_f32 v70, -v70, v73, v72
	v_div_fmas_f32 v70, v70, v71, v73
	v_div_fixup_f32 v69, v70, v69, 1.0
	v_div_scale_f32 v70, s[2:3], v68, v68, 1.0
	v_rcp_f32_e32 v71, v70
	s_nop 0
	v_fma_f32 v72, -v70, v71, 1.0
	v_fmac_f32_e32 v71, v72, v71
	v_div_scale_f32 v72, vcc, 1.0, v68, 1.0
	v_mul_f32_e32 v73, v72, v71
	v_fma_f32 v74, -v70, v73, v72
	v_fmac_f32_e32 v73, v74, v71
	v_fma_f32 v70, -v70, v73, v72
	v_div_fmas_f32 v70, v70, v71, v73
	v_div_fixup_f32 v68, v70, v68, 1.0
	v_pk_fma_f32 v[114:115], v[32:33], v[68:69], v[114:115]
	s_waitcnt vmcnt(14)
	v_cvt_f32_f16_e32 v68, v208
	v_cvt_f32_f16_e32 v69, v209
	v_mul_f32_e32 v68, 0xbfb8aa3b, v68
	v_mul_f32_e32 v69, 0xbfb8aa3b, v69
	v_exp_f32_e32 v68, v68
	v_exp_f32_e32 v69, v69
	s_nop 0
	v_pk_add_f32 v[68:69], v[68:69], 1.0 op_sel_hi:[1,0]
	s_nop 0
	v_div_scale_f32 v70, s[2:3], v69, v69, 1.0
	v_rcp_f32_e32 v71, v70
	s_nop 0
	v_fma_f32 v72, -v70, v71, 1.0
	v_fmac_f32_e32 v71, v72, v71
	v_div_scale_f32 v72, vcc, 1.0, v69, 1.0
	v_mul_f32_e32 v73, v72, v71
	v_fma_f32 v74, -v70, v73, v72
	v_fmac_f32_e32 v73, v74, v71
	v_fma_f32 v70, -v70, v73, v72
	v_div_fmas_f32 v70, v70, v71, v73
	v_div_fixup_f32 v69, v70, v69, 1.0
	v_div_scale_f32 v70, s[2:3], v68, v68, 1.0
	v_rcp_f32_e32 v71, v70
	s_nop 0
	v_fma_f32 v72, -v70, v71, 1.0
	v_fmac_f32_e32 v71, v72, v71
	v_div_scale_f32 v72, vcc, 1.0, v68, 1.0
	v_mul_f32_e32 v73, v72, v71
	v_fma_f32 v74, -v70, v73, v72
	v_fmac_f32_e32 v73, v74, v71
	v_fma_f32 v70, -v70, v73, v72
	v_div_fmas_f32 v70, v70, v71, v73
	v_div_fixup_f32 v68, v70, v68, 1.0
	v_pk_fma_f32 v[112:113], v[2:3], v[68:69], v[112:113]
	s_waitcnt vmcnt(12)
	v_cvt_f32_f16_e32 v68, v210
	v_cvt_f32_f16_e32 v69, v211
	v_mul_f32_e32 v68, 0xbfb8aa3b, v68
	v_mul_f32_e32 v69, 0xbfb8aa3b, v69
	v_exp_f32_e32 v68, v68
	v_exp_f32_e32 v69, v69
	s_nop 0
	v_pk_add_f32 v[68:69], v[68:69], 1.0 op_sel_hi:[1,0]
	s_nop 0
	v_div_scale_f32 v70, s[2:3], v69, v69, 1.0
	v_rcp_f32_e32 v71, v70
	s_nop 0
	v_fma_f32 v72, -v70, v71, 1.0
	v_fmac_f32_e32 v71, v72, v71
	v_div_scale_f32 v72, vcc, 1.0, v69, 1.0
	v_mul_f32_e32 v73, v72, v71
	v_fma_f32 v74, -v70, v73, v72
	v_fmac_f32_e32 v73, v74, v71
	v_fma_f32 v70, -v70, v73, v72
	v_div_fmas_f32 v70, v70, v71, v73
	v_div_fixup_f32 v69, v70, v69, 1.0
	v_div_scale_f32 v70, s[2:3], v68, v68, 1.0
	v_rcp_f32_e32 v71, v70
	s_nop 0
	v_fma_f32 v72, -v70, v71, 1.0
	v_fmac_f32_e32 v71, v72, v71
	v_div_scale_f32 v72, vcc, 1.0, v68, 1.0
	v_mul_f32_e32 v73, v72, v71
	v_fma_f32 v74, -v70, v73, v72
	v_fmac_f32_e32 v73, v74, v71
	v_fma_f32 v70, -v70, v73, v72
	v_div_fmas_f32 v70, v70, v71, v73
	v_div_fixup_f32 v68, v70, v68, 1.0
	v_pk_fma_f32 v[110:111], v[4:5], v[68:69], v[110:111]
	s_waitcnt vmcnt(10)
	v_cvt_f32_f16_e32 v68, v212
	v_cvt_f32_f16_e32 v69, v213
	v_mul_f32_e32 v68, 0xbfb8aa3b, v68
	v_mul_f32_e32 v69, 0xbfb8aa3b, v69
	v_exp_f32_e32 v68, v68
	v_exp_f32_e32 v69, v69
	s_nop 0
	v_pk_add_f32 v[68:69], v[68:69], 1.0 op_sel_hi:[1,0]
	s_nop 0
	v_div_scale_f32 v70, s[2:3], v69, v69, 1.0
	v_rcp_f32_e32 v71, v70
	s_nop 0
	v_fma_f32 v72, -v70, v71, 1.0
	v_fmac_f32_e32 v71, v72, v71
	v_div_scale_f32 v72, vcc, 1.0, v69, 1.0
	v_mul_f32_e32 v73, v72, v71
	v_fma_f32 v74, -v70, v73, v72
	v_fmac_f32_e32 v73, v74, v71
	v_fma_f32 v70, -v70, v73, v72
	v_div_fmas_f32 v70, v70, v71, v73
	v_div_fixup_f32 v69, v70, v69, 1.0
	v_div_scale_f32 v70, s[2:3], v68, v68, 1.0
	v_rcp_f32_e32 v71, v70
	s_nop 0
	v_fma_f32 v72, -v70, v71, 1.0
	v_fmac_f32_e32 v71, v72, v71
	v_div_scale_f32 v72, vcc, 1.0, v68, 1.0
	v_mul_f32_e32 v73, v72, v71
	v_fma_f32 v74, -v70, v73, v72
	v_fmac_f32_e32 v73, v74, v71
	v_fma_f32 v70, -v70, v73, v72
	v_div_fmas_f32 v70, v70, v71, v73
	v_div_fixup_f32 v68, v70, v68, 1.0
	v_pk_fma_f32 v[108:109], v[6:7], v[68:69], v[108:109]
	s_waitcnt vmcnt(8)
; __device__ __forceinline__ float sigmoidf_(float x) { return 1.f / (1.f + __expf(-x)); }
; template <int NI, class LA, class LB, class EP>
; __device__ __forceinline__ void gemm_tile(int K, LA loadA, LB loadB, EP epi, char* smem) {
;     ...
; #pragma unroll
;   for (int mi = 0; mi < 2; ++mi)
; #pragma unroll
;     for (int ni = 0; ni < NI; ++ni)
; #pragma unroll
;       for (int r = 0; r < 16; ++r) {
;         const int row = wm * 64 + mi * 32 + (r & 3) + 8 * (r >> 2) + 4 * (lane >> 5);
;         const int col = wn * (NI * 32) + ni * 32 + (lane & 31);
;         epi(mi, ni, r, row, col, acc[mi][ni][r]);
; __device__ __forceinline__ void phase_merge(const KP& p, char* smem, int* q, int xcc) {
;     ...
;           [&](int mi, int ni, int r, int row, int col, float v) {
;             const float gz = (float)G[(size_t)row * NU + col];
;             tot[mi][ni][r] += sigmoidf_(gz) * v;
;           },
	v_cvt_f32_f16_e32 v68, v214
	v_cvt_f32_f16_e32 v69, v215
	v_mul_f32_e32 v68, 0xbfb8aa3b, v68
	v_mul_f32_e32 v69, 0xbfb8aa3b, v69
	v_exp_f32_e32 v68, v68
	v_exp_f32_e32 v69, v69
	s_nop 0
	v_pk_add_f32 v[68:69], v[68:69], 1.0 op_sel_hi:[1,0]
	s_nop 0
	v_div_scale_f32 v70, s[2:3], v69, v69, 1.0
	v_rcp_f32_e32 v71, v70
	s_nop 0
	v_fma_f32 v72, -v70, v71, 1.0
	v_fmac_f32_e32 v71, v72, v71
	v_div_scale_f32 v72, vcc, 1.0, v69, 1.0
	v_mul_f32_e32 v73, v72, v71
	v_fma_f32 v74, -v70, v73, v72
	v_fmac_f32_e32 v73, v74, v71
	v_fma_f32 v70, -v70, v73, v72
	v_div_fmas_f32 v70, v70, v71, v73
	v_div_fixup_f32 v69, v70, v69, 1.0
	v_div_scale_f32 v70, s[2:3], v68, v68, 1.0
	v_rcp_f32_e32 v71, v70
	s_nop 0
	v_fma_f32 v72, -v70, v71, 1.0
	v_fmac_f32_e32 v71, v72, v71
	v_div_scale_f32 v72, vcc, 1.0, v68, 1.0
	v_mul_f32_e32 v73, v72, v71
	v_fma_f32 v74, -v70, v73, v72
	v_fmac_f32_e32 v73, v74, v71
	v_fma_f32 v70, -v70, v73, v72
	v_div_fmas_f32 v70, v70, v71, v73
	v_div_fixup_f32 v68, v70, v68, 1.0
	v_pk_fma_f32 v[106:107], v[8:9], v[68:69], v[106:107]
	s_waitcnt vmcnt(6)
	v_cvt_f32_f16_e32 v68, v216
	v_cvt_f32_f16_e32 v69, v217
	v_mul_f32_e32 v68, 0xbfb8aa3b, v68
	v_mul_f32_e32 v69, 0xbfb8aa3b, v69
	v_exp_f32_e32 v68, v68
	v_exp_f32_e32 v69, v69
	s_nop 0
	v_pk_add_f32 v[68:69], v[68:69], 1.0 op_sel_hi:[1,0]
	s_nop 0
	v_div_scale_f32 v70, s[2:3], v69, v69, 1.0
	v_rcp_f32_e32 v71, v70
	s_nop 0
	v_fma_f32 v72, -v70, v71, 1.0
	v_fmac_f32_e32 v71, v72, v71
	v_div_scale_f32 v72, vcc, 1.0, v69, 1.0
	v_mul_f32_e32 v73, v72, v71
	v_fma_f32 v74, -v70, v73, v72
	v_fmac_f32_e32 v73, v74, v71
	v_fma_f32 v70, -v70, v73, v72
	v_div_fmas_f32 v70, v70, v71, v73
	v_div_fixup_f32 v69, v70, v69, 1.0
	v_div_scale_f32 v70, s[2:3], v68, v68, 1.0
	v_rcp_f32_e32 v71, v70
	s_nop 0
	v_fma_f32 v72, -v70, v71, 1.0
	v_fmac_f32_e32 v71, v72, v71
	v_div_scale_f32 v72, vcc, 1.0, v68, 1.0
	v_mul_f32_e32 v73, v72, v71
	v_fma_f32 v74, -v70, v73, v72
	v_fmac_f32_e32 v73, v74, v71
	v_fma_f32 v70, -v70, v73, v72
	v_div_fmas_f32 v70, v70, v71, v73
	v_div_fixup_f32 v68, v70, v68, 1.0
	v_pk_fma_f32 v[104:105], v[10:11], v[68:69], v[104:105]
	s_waitcnt vmcnt(4)
	v_cvt_f32_f16_e32 v68, v218
	v_cvt_f32_f16_e32 v69, v219
	v_mul_f32_e32 v68, 0xbfb8aa3b, v68
	v_mul_f32_e32 v69, 0xbfb8aa3b, v69
	v_exp_f32_e32 v68, v68
	v_exp_f32_e32 v69, v69
	s_nop 0
	v_pk_add_f32 v[68:69], v[68:69], 1.0 op_sel_hi:[1,0]
	s_nop 0
	v_div_scale_f32 v70, s[2:3], v69, v69, 1.0
	v_rcp_f32_e32 v71, v70
	s_nop 0
	v_fma_f32 v72, -v70, v71, 1.0
	v_fmac_f32_e32 v71, v72, v71
	v_div_scale_f32 v72, vcc, 1.0, v69, 1.0
	v_mul_f32_e32 v73, v72, v71
	v_fma_f32 v74, -v70, v73, v72
	v_fmac_f32_e32 v73, v74, v71
	v_fma_f32 v70, -v70, v73, v72
	v_div_fmas_f32 v70, v70, v71, v73
	v_div_fixup_f32 v69, v70, v69, 1.0
	v_div_scale_f32 v70, s[2:3], v68, v68, 1.0
	v_rcp_f32_e32 v71, v70
	s_nop 0
	v_fma_f32 v72, -v70, v71, 1.0
	v_fmac_f32_e32 v71, v72, v71
	v_div_scale_f32 v72, vcc, 1.0, v68, 1.0
	v_mul_f32_e32 v73, v72, v71
	v_fma_f32 v74, -v70, v73, v72
	v_fmac_f32_e32 v73, v74, v71
	v_fma_f32 v70, -v70, v73, v72
	v_div_fmas_f32 v70, v70, v71, v73
	v_div_fixup_f32 v68, v70, v68, 1.0
	v_pk_fma_f32 v[102:103], v[12:13], v[68:69], v[102:103]
	s_waitcnt vmcnt(2)
	v_cvt_f32_f16_e32 v68, v220
	v_cvt_f32_f16_e32 v69, v221
	v_mul_f32_e32 v68, 0xbfb8aa3b, v68
	v_mul_f32_e32 v69, 0xbfb8aa3b, v69
	v_exp_f32_e32 v68, v68
	v_exp_f32_e32 v69, v69
	s_nop 0
	v_pk_add_f32 v[68:69], v[68:69], 1.0 op_sel_hi:[1,0]
	s_nop 0
	v_div_scale_f32 v70, s[2:3], v69, v69, 1.0
	v_rcp_f32_e32 v71, v70
	s_nop 0
	v_fma_f32 v72, -v70, v71, 1.0
	v_fmac_f32_e32 v71, v72, v71
	v_div_scale_f32 v72, vcc, 1.0, v69, 1.0
	v_mul_f32_e32 v73, v72, v71
	v_fma_f32 v74, -v70, v73, v72
	v_fmac_f32_e32 v73, v74, v71
	v_fma_f32 v70, -v70, v73, v72
	v_div_fmas_f32 v70, v70, v71, v73
	v_div_fixup_f32 v69, v70, v69, 1.0
	v_div_scale_f32 v70, s[2:3], v68, v68, 1.0
	v_rcp_f32_e32 v71, v70
	s_nop 0
	v_fma_f32 v72, -v70, v71, 1.0
	v_fmac_f32_e32 v71, v72, v71
	v_div_scale_f32 v72, vcc, 1.0, v68, 1.0
	v_mul_f32_e32 v73, v72, v71
	v_fma_f32 v74, -v70, v73, v72
	v_fmac_f32_e32 v73, v74, v71
	v_fma_f32 v70, -v70, v73, v72
	v_div_fmas_f32 v70, v70, v71, v73
	v_div_fixup_f32 v68, v70, v68, 1.0
	v_pk_fma_f32 v[100:101], v[14:15], v[68:69], v[100:101]
	s_waitcnt vmcnt(0)
	v_cvt_f32_f16_e32 v68, v222
	v_cvt_f32_f16_e32 v69, v223
	v_mul_f32_e32 v68, 0xbfb8aa3b, v68
	v_mul_f32_e32 v69, 0xbfb8aa3b, v69
	v_exp_f32_e32 v68, v68
	v_exp_f32_e32 v69, v69
	s_nop 0
	v_pk_add_f32 v[68:69], v[68:69], 1.0 op_sel_hi:[1,0]
	s_nop 0
	v_div_scale_f32 v70, s[2:3], v69, v69, 1.0
	v_rcp_f32_e32 v71, v70
	s_nop 0
	v_fma_f32 v72, -v70, v71, 1.0
	v_fmac_f32_e32 v71, v72, v71
	v_div_scale_f32 v72, vcc, 1.0, v69, 1.0
	v_mul_f32_e32 v73, v72, v71
	v_fma_f32 v74, -v70, v73, v72
	v_fmac_f32_e32 v73, v74, v71
	v_fma_f32 v70, -v70, v73, v72
	v_div_fmas_f32 v70, v70, v71, v73
	v_div_fixup_f32 v69, v70, v69, 1.0
	v_div_scale_f32 v70, s[2:3], v68, v68, 1.0
	v_rcp_f32_e32 v71, v70
	s_nop 0
	v_fma_f32 v72, -v70, v71, 1.0
	v_fmac_f32_e32 v71, v72, v71
	v_div_scale_f32 v72, vcc, 1.0, v68, 1.0
	v_mul_f32_e32 v73, v72, v71
	v_fma_f32 v74, -v70, v73, v72
	v_fmac_f32_e32 v73, v74, v71
	v_fma_f32 v70, -v70, v73, v72
	v_div_fmas_f32 v70, v70, v71, v73
	v_div_fixup_f32 v68, v70, v68, 1.0
	v_pk_fma_f32 v[98:99], v[16:17], v[68:69], v[98:99]
	s_cmp_lg_u32 s56, 3
	s_cbranch_scc1 .LBB0_1742
;   __device__ __forceinline__ const float* x() const { return (const float*)(const __attribute__((address_space(1))) float*)kp[0]; }
;   __device__ __forceinline__ half_t* mm() const { return (half_t*)(ws() + OFF_mm); }
; __device__ __forceinline__ void phase_merge(const KP& p, char* smem, int* q, int xcc) {
;     ...
;     int tidx = threadIdx.x;
;     asm volatile("" : "+v"(tidx));
;     const int lane = tidx & 63, wid = tidx >> 6, wm = wid >> 1, wn = wid & 1;
; #pragma unroll
;     for (int mi = 0; mi < 2; ++mi)
; #pragma unroll
;       for (int ni = 0; ni < 2; ++ni)
; #pragma unroll
;         for (int r = 0; r < 16; ++r) {
;           const int row = wm * 64 + mi * 32 + (r & 3) + 8 * (r >> 2) + 4 * (lane >> 5);
;           const int col = wn * 64 + ni * 32 + (lane & 31);
;           p.mm()[(size_t)(m0 + row) * DM + n0 + col] = (half_t)tot[mi][ni][r];
;         }
	v_mov_b32_e32 v0, v224
	v_ashrrev_i32_e32 v2, 1, v0
	v_and_b32_e32 v2, 0xffffffc0, v2
	v_lshrrev_b32_e32 v3, 3, v0
	v_add_u32_e32 v2, s14, v2
	v_and_or_b32 v2, v3, 4, v2
	v_and_b32_e32 v3, 31, v0
	v_bfe_u32 v4, v0, 6, 1
	v_lshlrev_b32_e32 v3, 1, v3
	v_lshl_or_b32 v3, v4, 21, v3
	v_lshl_add_u32 v4, v2, 6, v3
	s_lshr_b32 s2, s18, 6
	s_lshl_b32 s2, s2, 20
	s_add_u32 s2, s44, s2
	s_addc_u32 s3, s45, 0
	s_add_u32 s40, s2, 0x100000
	s_addc_u32 s41, s3, 0
	v_cvt_f16_f32_e32 v5, v160
	global_store_short v4, v5, s[2:3]
	v_cvt_f16_f32_e32 v6, v161
	global_store_short v4, v6, s[2:3] offset:64
	v_cvt_f16_f32_e32 v7, v158
	global_store_short v4, v7, s[2:3] offset:128
	v_cvt_f16_f32_e32 v8, v159
	global_store_short v4, v8, s[2:3] offset:192
	v_cvt_f16_f32_e32 v9, v156
	global_store_short v4, v9, s[2:3] offset:512
	v_cvt_f16_f32_e32 v10, v157
	global_store_short v4, v10, s[2:3] offset:576
	v_cvt_f16_f32_e32 v11, v154
	global_store_short v4, v11, s[2:3] offset:640
	v_cvt_f16_f32_e32 v12, v155
	global_store_short v4, v12, s[2:3] offset:704
	v_cvt_f16_f32_e32 v5, v152
	global_store_short v4, v5, s[2:3] offset:1024
	v_cvt_f16_f32_e32 v6, v153
	global_store_short v4, v6, s[2:3] offset:1088
	v_cvt_f16_f32_e32 v7, v150
	global_store_short v4, v7, s[2:3] offset:1152
	v_cvt_f16_f32_e32 v8, v151
	global_store_short v4, v8, s[2:3] offset:1216
	v_cvt_f16_f32_e32 v9, v148
	global_store_short v4, v9, s[2:3] offset:1536
	v_cvt_f16_f32_e32 v10, v149
	global_store_short v4, v10, s[2:3] offset:1600
	v_cvt_f16_f32_e32 v11, v146
	global_store_short v4, v11, s[2:3] offset:1664
	v_cvt_f16_f32_e32 v12, v147
	global_store_short v4, v12, s[2:3] offset:1728
	v_cvt_f16_f32_e32 v5, v144
	global_store_short v4, v5, s[40:41]
	v_cvt_f16_f32_e32 v6, v145
	global_store_short v4, v6, s[40:41] offset:64
	v_cvt_f16_f32_e32 v7, v142
	global_store_short v4, v7, s[40:41] offset:128
	v_cvt_f16_f32_e32 v8, v143
	global_store_short v4, v8, s[40:41] offset:192
	v_cvt_f16_f32_e32 v9, v140
	global_store_short v4, v9, s[40:41] offset:512
	v_cvt_f16_f32_e32 v10, v141
	global_store_short v4, v10, s[40:41] offset:576
	v_cvt_f16_f32_e32 v11, v138
	global_store_short v4, v11, s[40:41] offset:640
	v_cvt_f16_f32_e32 v12, v139
	global_store_short v4, v12, s[40:41] offset:704
	v_cvt_f16_f32_e32 v5, v136
	global_store_short v4, v5, s[40:41] offset:1024
	v_cvt_f16_f32_e32 v6, v137
	global_store_short v4, v6, s[40:41] offset:1088
	v_cvt_f16_f32_e32 v7, v134
	global_store_short v4, v7, s[40:41] offset:1152
	v_cvt_f16_f32_e32 v8, v135
	global_store_short v4, v8, s[40:41] offset:1216
	v_cvt_f16_f32_e32 v9, v132
	global_store_short v4, v9, s[40:41] offset:1536
	v_cvt_f16_f32_e32 v10, v133
	global_store_short v4, v10, s[40:41] offset:1600
	v_cvt_f16_f32_e32 v11, v130
	global_store_short v4, v11, s[40:41] offset:1664
	v_cvt_f16_f32_e32 v12, v131
	global_store_short v4, v12, s[40:41] offset:1728
	v_cvt_f16_f32_e32 v5, v128
	global_store_short v4, v5, s[2:3] offset:2048
	v_cvt_f16_f32_e32 v6, v129
	global_store_short v4, v6, s[2:3] offset:2112
	v_cvt_f16_f32_e32 v7, v126
	global_store_short v4, v7, s[2:3] offset:2176
	v_cvt_f16_f32_e32 v8, v127
	global_store_short v4, v8, s[2:3] offset:2240
	v_cvt_f16_f32_e32 v9, v124
	global_store_short v4, v9, s[2:3] offset:2560
	v_cvt_f16_f32_e32 v10, v125
	global_store_short v4, v10, s[2:3] offset:2624
	v_cvt_f16_f32_e32 v11, v122
	global_store_short v4, v11, s[2:3] offset:2688
	v_cvt_f16_f32_e32 v12, v123
	global_store_short v4, v12, s[2:3] offset:2752
	v_cvt_f16_f32_e32 v5, v120
	global_store_short v4, v5, s[2:3] offset:3072
	v_cvt_f16_f32_e32 v6, v121
	global_store_short v4, v6, s[2:3] offset:3136
	v_cvt_f16_f32_e32 v7, v118
	global_store_short v4, v7, s[2:3] offset:3200
	v_cvt_f16_f32_e32 v8, v119
	global_store_short v4, v8, s[2:3] offset:3264
	v_cvt_f16_f32_e32 v9, v116
	global_store_short v4, v9, s[2:3] offset:3584
	v_cvt_f16_f32_e32 v10, v117
	global_store_short v4, v10, s[2:3] offset:3648
	v_cvt_f16_f32_e32 v11, v114
	global_store_short v4, v11, s[2:3] offset:3712
	v_cvt_f16_f32_e32 v12, v115
	global_store_short v4, v12, s[2:3] offset:3776
	v_cvt_f16_f32_e32 v5, v112
	global_store_short v4, v5, s[40:41] offset:2048
	v_cvt_f16_f32_e32 v6, v113
	global_store_short v4, v6, s[40:41] offset:2112
	v_cvt_f16_f32_e32 v7, v110
	global_store_short v4, v7, s[40:41] offset:2176
	v_cvt_f16_f32_e32 v8, v111
	global_store_short v4, v8, s[40:41] offset:2240
	v_cvt_f16_f32_e32 v9, v108
	global_store_short v4, v9, s[40:41] offset:2560
	v_cvt_f16_f32_e32 v10, v109
	global_store_short v4, v10, s[40:41] offset:2624
	v_cvt_f16_f32_e32 v11, v106
	global_store_short v4, v11, s[40:41] offset:2688
	v_cvt_f16_f32_e32 v12, v107
	global_store_short v4, v12, s[40:41] offset:2752
	v_cvt_f16_f32_e32 v5, v104
	global_store_short v4, v5, s[40:41] offset:3072
	v_cvt_f16_f32_e32 v6, v105
	global_store_short v4, v6, s[40:41] offset:3136
	v_cvt_f16_f32_e32 v7, v102
	global_store_short v4, v7, s[40:41] offset:3200
	v_cvt_f16_f32_e32 v8, v103
	global_store_short v4, v8, s[40:41] offset:3264
	v_cvt_f16_f32_e32 v9, v100
	global_store_short v4, v9, s[40:41] offset:3584
	v_cvt_f16_f32_e32 v10, v101
	global_store_short v4, v10, s[40:41] offset:3648
	v_cvt_f16_f32_e32 v11, v98
	global_store_short v4, v11, s[40:41] offset:3712
	v_cvt_f16_f32_e32 v12, v99
	global_store_short v4, v12, s[40:41] offset:3776
	s_branch .LBB0_1731
